# GEMM K-loops without the per-phase s_setprio 1/0 flips (64 instructions), on top of the SGPR-base DMA addressing
# speedup vs baseline: 1.0031x; 1.0031x over previous
; #define PG8_STAGE(bufoff, gbase, voff) do { _Pragma("unroll") for (int _i = 0; _i < 2; ++_i) \
;         __builtin_amdgcn_global_load_lds((const unsigned*)((const char*)(gbase) + (voff)[_i]), (PG8_LAS unsigned*)(lds + (bufoff) + ldsw + _i * 8192), 16, 0, 0); } while (0)
; #define PG8_LDA(dst, b, h) do { _Pragma("unroll") for (int m = 0; m < 4; ++m) _Pragma("unroll") for (int k = 0; k < 2; ++k) dst[m][k] = *(const PG8_LAS bf16x8*)(lds + PG8_SA(b, h) + aoff + m * 2048 + k * 1024); } while (0)
; #define PG8_LDB(dst, b, h) do { _Pragma("unroll") for (int n = 0; n < 2; ++n) _Pragma("unroll") for (int k = 0; k < 2; ++k) dst[n][k] = *(const PG8_LAS bf16x8*)(lds + PG8_SB(b, h) + boff + n * 2048 + k * 1024); } while (0)
; #define PG8_WAIT_V(n) asm volatile("s_waitcnt vmcnt(" #n ")" ::: "memory")
; #define PG8_WAIT_L(n) asm volatile("s_waitcnt lgkmcnt(" #n ")" ::: "memory")
; #define PG8_BAR __builtin_amdgcn_s_barrier()
; #define PG8_SCHED __builtin_amdgcn_sched_barrier(0)
; template <class Epi, class Sched>
; __device__ __forceinline__ void gemm_phase(PG8_LAS unsigned char* lds, const Gemm g, const Sched& S, const Epi& E) {
;     ...
;         const bool has_next = S.next(ui + 1, nxt);
;         const char* nA = has_next ? (const char*)g.A + (size_t)nxt.pm * tstep : cA; const char* nB = has_next ? (const char*)g.Bt + (size_t)nxt.pn * tstep : cB;
;         for (int t = 0; t < nt; t += 2) {
;             const bool last = (t == nt - 2);
;             const char* a1 = cA + (size_t)(t + 1) * kstep;
;             const char* a2 = last ? nA : cA + (size_t)(t + 2) * kstep; const char* b2 = last ? nB : cB + (size_t)(t + 2) * kstep;
;             const char* a3 = a2 + kstep; const char* b3 = b2 + kstep;
;             if (last && has_next) S.a_ready(nxt);
;             PG8_LDB(B0, 0, 0); PG8_SCHED; PG8_LDA(At, 0, 0); PG8_STAGE(PG8_SA(1, 1), a1 + hstep, voffA);
;             PG8_WAIT_L(8); PG8_BAR; PG8_WAIT_L(0); PG8_MMA(0, 0, At, B0); PG8_BAR; PG8_SCHED;
;             PG8_LDB(B1, 0, 1); PG8_STAGE(PG8_SB(0, 0), b2, voffB);
;             PG8_BAR; PG8_WAIT_L(0); PG8_MMA(0, 1, At, B1); PG8_BAR;
;             PG8_LDA(At, 0, 1); PG8_STAGE(PG8_SA(0, 0), a2, voffA);
;             PG8_BAR; PG8_WAIT_L(0); PG8_MMA(1, 0, At, B0); PG8_BAR; PG8_SCHED;
;             PG8_STAGE(PG8_SB(0, 1), b2 + hstep, voffB);
;             PG8_WAIT_V(6); PG8_BAR; PG8_MMA(1, 1, At, B1); PG8_BAR;
.LBB0_96:
	s_add_u32 s10, s8, 0x100
	s_addc_u32 s11, s9, 0
	s_add_i32 s46, 0, 0x10000
	v_add_u32_e32 v154, s46, v139
	ds_read_b128 v[142:145], v154
	ds_read_b128 v[146:149], v154 offset:1024
	ds_read_b128 v[150:153], v154 offset:2048
	ds_read_b128 v[154:157], v154 offset:3072
	s_cmp_eq_u32 s45, 40
	s_cselect_b32 s15, s1, s11
	s_cselect_b32 s14, s0, s10
	s_cselect_b32 s13, s5, s44
	s_cselect_b32 s12, s4, s43
	s_add_i32 m0, s20, 0xc000
	ds_read_b128 v[158:161], v141
	ds_read_b128 v[162:165], v141 offset:1024
	ds_read_b128 v[166:169], v141 offset:2048
	ds_read_b128 v[170:173], v141 offset:3072
	ds_read_b128 v[178:181], v141 offset:4096
	ds_read_b128 v[182:185], v141 offset:5120
	ds_read_b128 v[186:189], v141 offset:6144
	ds_read_b128 v[190:193], v141 offset:7168
	global_load_lds_dwordx4 v134, s[8:9]
	s_add_i32 m0, s20, 0xe000
	s_nop 0
	global_load_lds_dwordx4 v136, s[8:9]
	s_waitcnt lgkmcnt(8)
	s_barrier
	s_waitcnt lgkmcnt(0)
	v_mfma_f32_16x16x32_bf16 v[124:127], v[142:145], v[158:161], v[124:127]
	v_mfma_f32_16x16x32_bf16 v[120:123], v[150:153], v[158:161], v[120:123]
	v_mfma_f32_16x16x32_bf16 v[116:119], v[142:145], v[166:169], v[116:119]
	v_mfma_f32_16x16x32_bf16 v[112:115], v[150:153], v[166:169], v[112:115]
	v_mfma_f32_16x16x32_bf16 v[100:103], v[142:145], v[178:181], v[100:103]
	v_mfma_f32_16x16x32_bf16 v[96:99], v[150:153], v[178:181], v[96:99]
	v_mfma_f32_16x16x32_bf16 v[84:87], v[142:145], v[186:189], v[84:87]
	v_mfma_f32_16x16x32_bf16 v[80:83], v[150:153], v[186:189], v[80:83]
	v_mfma_f32_16x16x32_bf16 v[124:127], v[146:149], v[162:165], v[124:127]
	v_mfma_f32_16x16x32_bf16 v[120:123], v[154:157], v[162:165], v[120:123]
	v_mfma_f32_16x16x32_bf16 v[116:119], v[146:149], v[170:173], v[116:119]
	v_mfma_f32_16x16x32_bf16 v[112:115], v[154:157], v[170:173], v[112:115]
	v_mfma_f32_16x16x32_bf16 v[100:103], v[146:149], v[182:185], v[100:103]
	v_mfma_f32_16x16x32_bf16 v[96:99], v[154:157], v[182:185], v[96:99]
	v_mfma_f32_16x16x32_bf16 v[84:87], v[146:149], v[190:193], v[84:87]
	v_mfma_f32_16x16x32_bf16 v[80:83], v[154:157], v[190:193], v[80:83]
	s_barrier
	s_add_i32 s47, 0, 0x14000
	v_add_u32_e32 v174, s47, v139
	s_add_i32 s8, s46, s18
	ds_read_b128 v[194:197], v174
	ds_read_b128 v[198:201], v174 offset:1024
	ds_read_b128 v[202:205], v174 offset:2048
	ds_read_b128 v[206:209], v174 offset:3072
	s_add_u32 s98, s12, 0x80
	s_addc_u32 s99, s13, 0
	s_mov_b32 m0, s8
	s_nop 0
	global_load_lds_dwordx4 v176, s[12:13]
	s_add_i32 m0, s8, 0x2000
	s_nop 0
	global_load_lds_dwordx4 v128, s[12:13]
	s_barrier
	s_waitcnt lgkmcnt(0)
	v_mfma_f32_16x16x32_bf16 v[108:111], v[194:197], v[158:161], v[108:111]
	v_mfma_f32_16x16x32_bf16 v[104:107], v[202:205], v[158:161], v[104:107]
	v_mfma_f32_16x16x32_bf16 v[92:95], v[194:197], v[166:169], v[92:95]
	v_mfma_f32_16x16x32_bf16 v[88:91], v[202:205], v[166:169], v[88:91]
	v_mfma_f32_16x16x32_bf16 v[76:79], v[194:197], v[178:181], v[76:79]
	v_mfma_f32_16x16x32_bf16 v[72:75], v[202:205], v[178:181], v[72:75]
	v_mfma_f32_16x16x32_bf16 v[68:71], v[194:197], v[186:189], v[68:71]
	v_mfma_f32_16x16x32_bf16 v[64:67], v[202:205], v[186:189], v[64:67]
	v_mfma_f32_16x16x32_bf16 v[108:111], v[198:201], v[162:165], v[108:111]
	v_mfma_f32_16x16x32_bf16 v[104:107], v[206:209], v[162:165], v[104:107]
	v_mfma_f32_16x16x32_bf16 v[92:95], v[198:201], v[170:173], v[92:95]
	v_mfma_f32_16x16x32_bf16 v[88:91], v[206:209], v[170:173], v[88:91]
	v_mfma_f32_16x16x32_bf16 v[76:79], v[198:201], v[182:185], v[76:79]
	v_mfma_f32_16x16x32_bf16 v[72:75], v[206:209], v[182:185], v[72:75]
	v_mfma_f32_16x16x32_bf16 v[68:71], v[198:201], v[190:193], v[68:71]
	v_mfma_f32_16x16x32_bf16 v[64:67], v[206:209], v[190:193], v[64:67]
	s_mov_b32 m0, s20
	s_add_u32 s100, s14, 0x80
	s_addc_u32 s101, s15, 0
	s_barrier
	ds_read_b128 v[158:161], v141 offset:16384
	ds_read_b128 v[162:165], v141 offset:17408
	ds_read_b128 v[166:169], v141 offset:18432
	ds_read_b128 v[170:173], v141 offset:19456
	ds_read_b128 v[178:181], v141 offset:20480
	ds_read_b128 v[182:185], v141 offset:21504
	ds_read_b128 v[186:189], v141 offset:22528
	ds_read_b128 v[190:193], v141 offset:23552
	global_load_lds_dwordx4 v132, s[14:15]
	s_mov_b32 m0, s21
	s_nop 0
	global_load_lds_dwordx4 v130, s[14:15]
	s_barrier
	s_waitcnt lgkmcnt(0)
	v_mfma_f32_16x16x32_bf16 v[60:63], v[142:145], v[158:161], v[60:63]
	v_mfma_f32_16x16x32_bf16 v[56:59], v[150:153], v[158:161], v[56:59]
	v_mfma_f32_16x16x32_bf16 v[52:55], v[142:145], v[166:169], v[52:55]
	v_mfma_f32_16x16x32_bf16 v[48:51], v[150:153], v[166:169], v[48:51]
	v_mfma_f32_16x16x32_bf16 v[36:39], v[142:145], v[178:181], v[36:39]
	v_mfma_f32_16x16x32_bf16 v[32:35], v[150:153], v[178:181], v[32:35]
	v_mfma_f32_16x16x32_bf16 v[20:23], v[142:145], v[186:189], v[20:23]
	v_mfma_f32_16x16x32_bf16 v[16:19], v[150:153], v[186:189], v[16:19]
	v_mfma_f32_16x16x32_bf16 v[60:63], v[146:149], v[162:165], v[60:63]
	v_mfma_f32_16x16x32_bf16 v[56:59], v[154:157], v[162:165], v[56:59]
	v_mfma_f32_16x16x32_bf16 v[52:55], v[146:149], v[170:173], v[52:55]
	v_mfma_f32_16x16x32_bf16 v[48:51], v[154:157], v[170:173], v[48:51]
	v_mfma_f32_16x16x32_bf16 v[36:39], v[146:149], v[182:185], v[36:39]
	v_mfma_f32_16x16x32_bf16 v[32:35], v[154:157], v[182:185], v[32:35]
	v_mfma_f32_16x16x32_bf16 v[20:23], v[146:149], v[190:193], v[20:23]
	v_mfma_f32_16x16x32_bf16 v[16:19], v[154:157], v[190:193], v[16:19]
	s_barrier
	s_add_u32 s8, s12, 0xb0000
	s_addc_u32 s9, s13, 0
	s_add_i32 s46, s47, s18
	s_mov_b32 m0, s46
	s_nop 0
	global_load_lds_dwordx4 v176, s[8:9]
	s_add_i32 m0, s46, 0x2000
	s_nop 0
	global_load_lds_dwordx4 v128, s[8:9]
	s_waitcnt vmcnt(6)
	s_barrier
; #define PG8_STAGE(bufoff, gbase, voff) do { _Pragma("unroll") for (int _i = 0; _i < 2; ++_i) \
;         __builtin_amdgcn_global_load_lds((const unsigned*)((const char*)(gbase) + (voff)[_i]), (PG8_LAS unsigned*)(lds + (bufoff) + ldsw + _i * 8192), 16, 0, 0); } while (0)
; #define PG8_LDA(dst, b, h) do { _Pragma("unroll") for (int m = 0; m < 4; ++m) _Pragma("unroll") for (int k = 0; k < 2; ++k) dst[m][k] = *(const PG8_LAS bf16x8*)(lds + PG8_SA(b, h) + aoff + m * 2048 + k * 1024); } while (0)
; #define PG8_LDB(dst, b, h) do { _Pragma("unroll") for (int n = 0; n < 2; ++n) _Pragma("unroll") for (int k = 0; k < 2; ++k) dst[n][k] = *(const PG8_LAS bf16x8*)(lds + PG8_SB(b, h) + boff + n * 2048 + k * 1024); } while (0)
; #define PG8_MMA(ai, bj, At, Bt) do { __builtin_amdgcn_s_setprio(1); _Pragma("unroll") for (int m = 0; m < 4; ++m) _Pragma("unroll") for (int n = 0; n < 2; ++n) _Pragma("unroll") for (int k = 0; k < 2; ++k) \
;         acc[ai][bj][m][n] = __builtin_amdgcn_mfma_f32_16x16x32_bf16(Bt[n][k], At[m][k], acc[ai][bj][m][n], 0, 0, 0); __builtin_amdgcn_s_setprio(0); } while (0)
; #define PG8_WAIT_V(n) asm volatile("s_waitcnt vmcnt(" #n ")" ::: "memory")
; #define PG8_WAIT_L(n) asm volatile("s_waitcnt lgkmcnt(" #n ")" ::: "memory")
; #define PG8_BAR __builtin_amdgcn_s_barrier()
; #define PG8_SCHED __builtin_amdgcn_sched_barrier(0)
; template <class Epi, class Sched>
; __device__ __forceinline__ void gemm_phase(PG8_LAS unsigned char* lds, const Gemm g, const Sched& S, const Epi& E) {
;     ...
;             PG8_WAIT_V(6); PG8_BAR; PG8_MMA(1, 1, At, B1); PG8_BAR;
;             PG8_LDB(B0, 1, 0); PG8_SCHED; PG8_LDA(At, 1, 0); PG8_STAGE(PG8_SA(0, 1), a2 + hstep, voffA);
;             PG8_WAIT_L(8); PG8_BAR; PG8_WAIT_L(0); PG8_MMA(0, 0, At, B0); PG8_BAR; PG8_SCHED;
;             PG8_LDB(B1, 1, 1); PG8_STAGE(PG8_SB(1, 0), b3, voffB);
;             PG8_BAR; PG8_WAIT_L(0); PG8_MMA(0, 1, At, B1); PG8_BAR;
;             PG8_LDA(At, 1, 1); PG8_STAGE(PG8_SA(1, 0), a3, voffA);
	v_mfma_f32_16x16x32_bf16 v[44:47], v[194:197], v[158:161], v[44:47]
	v_mfma_f32_16x16x32_bf16 v[40:43], v[202:205], v[158:161], v[40:43]
	v_mfma_f32_16x16x32_bf16 v[28:31], v[194:197], v[166:169], v[28:31]
	v_mfma_f32_16x16x32_bf16 v[24:27], v[202:205], v[166:169], v[24:27]
	v_mfma_f32_16x16x32_bf16 v[12:15], v[194:197], v[178:181], v[12:15]
	v_mfma_f32_16x16x32_bf16 v[8:11], v[202:205], v[178:181], v[8:11]
	v_mfma_f32_16x16x32_bf16 v[4:7], v[194:197], v[186:189], v[4:7]
	v_mfma_f32_16x16x32_bf16 v[0:3], v[202:205], v[186:189], v[0:3]
	v_mfma_f32_16x16x32_bf16 v[44:47], v[198:201], v[162:165], v[44:47]
	v_mfma_f32_16x16x32_bf16 v[40:43], v[206:209], v[162:165], v[40:43]
	v_mfma_f32_16x16x32_bf16 v[28:31], v[198:201], v[170:173], v[28:31]
	v_mfma_f32_16x16x32_bf16 v[24:27], v[206:209], v[170:173], v[24:27]
	v_mfma_f32_16x16x32_bf16 v[12:15], v[198:201], v[182:185], v[12:15]
	v_mfma_f32_16x16x32_bf16 v[8:11], v[206:209], v[182:185], v[8:11]
	v_mfma_f32_16x16x32_bf16 v[4:7], v[198:201], v[190:193], v[4:7]
	v_mfma_f32_16x16x32_bf16 v[0:3], v[206:209], v[190:193], v[0:3]
	s_add_i32 s46, 0, 0x18000
	v_add_u32_e32 v154, s46, v139
	s_barrier
	ds_read_b128 v[142:145], v154
	ds_read_b128 v[146:149], v154 offset:1024
	ds_read_b128 v[150:153], v154 offset:2048
	ds_read_b128 v[154:157], v154 offset:3072
	s_add_u32 s8, s14, 0xb0000
	s_addc_u32 s9, s15, 0
	s_mov_b32 m0, s22
	ds_read_b128 v[158:161], v141 offset:32768
	ds_read_b128 v[162:165], v141 offset:33792
	ds_read_b128 v[166:169], v141 offset:34816
	ds_read_b128 v[170:173], v141 offset:35840
	ds_read_b128 v[178:181], v141 offset:36864
	ds_read_b128 v[182:185], v141 offset:37888
	ds_read_b128 v[186:189], v141 offset:38912
	ds_read_b128 v[190:193], v141 offset:39936
	global_load_lds_dwordx4 v132, s[8:9]
	s_mov_b32 m0, s23
	s_nop 0
	global_load_lds_dwordx4 v130, s[8:9]
	s_waitcnt lgkmcnt(8)
	s_barrier
	s_waitcnt lgkmcnt(0)
	v_mfma_f32_16x16x32_bf16 v[124:127], v[142:145], v[158:161], v[124:127]
	v_mfma_f32_16x16x32_bf16 v[120:123], v[150:153], v[158:161], v[120:123]
	v_mfma_f32_16x16x32_bf16 v[116:119], v[142:145], v[166:169], v[116:119]
	v_mfma_f32_16x16x32_bf16 v[112:115], v[150:153], v[166:169], v[112:115]
	v_mfma_f32_16x16x32_bf16 v[100:103], v[142:145], v[178:181], v[100:103]
	v_mfma_f32_16x16x32_bf16 v[96:99], v[150:153], v[178:181], v[96:99]
	v_mfma_f32_16x16x32_bf16 v[84:87], v[142:145], v[186:189], v[84:87]
	v_mfma_f32_16x16x32_bf16 v[80:83], v[150:153], v[186:189], v[80:83]
	v_mfma_f32_16x16x32_bf16 v[124:127], v[146:149], v[162:165], v[124:127]
	v_mfma_f32_16x16x32_bf16 v[120:123], v[154:157], v[162:165], v[120:123]
	v_mfma_f32_16x16x32_bf16 v[116:119], v[146:149], v[170:173], v[116:119]
	v_mfma_f32_16x16x32_bf16 v[112:115], v[154:157], v[170:173], v[112:115]
	v_mfma_f32_16x16x32_bf16 v[100:103], v[146:149], v[182:185], v[100:103]
	v_mfma_f32_16x16x32_bf16 v[96:99], v[154:157], v[182:185], v[96:99]
	v_mfma_f32_16x16x32_bf16 v[84:87], v[146:149], v[190:193], v[84:87]
	v_mfma_f32_16x16x32_bf16 v[80:83], v[154:157], v[190:193], v[80:83]
	s_barrier
	s_add_i32 s14, 0, 0x1c000
	s_add_i32 s8, s46, s18
	v_add_u32_e32 v206, s14, v139
	s_mov_b32 m0, s8
	ds_read_b128 v[194:197], v206
	ds_read_b128 v[198:201], v206 offset:1024
	ds_read_b128 v[202:205], v206 offset:2048
	ds_read_b128 v[206:209], v206 offset:3072
	global_load_lds_dwordx4 v176, s[98:99]
	s_add_i32 m0, s8, 0x2000
	s_nop 0
	global_load_lds_dwordx4 v128, s[98:99]
	s_barrier
	s_waitcnt lgkmcnt(0)
	v_mfma_f32_16x16x32_bf16 v[108:111], v[194:197], v[158:161], v[108:111]
	v_mfma_f32_16x16x32_bf16 v[104:107], v[202:205], v[158:161], v[104:107]
	v_mfma_f32_16x16x32_bf16 v[92:95], v[194:197], v[166:169], v[92:95]
	v_mfma_f32_16x16x32_bf16 v[88:91], v[202:205], v[166:169], v[88:91]
	v_mfma_f32_16x16x32_bf16 v[76:79], v[194:197], v[178:181], v[76:79]
	v_mfma_f32_16x16x32_bf16 v[72:75], v[202:205], v[178:181], v[72:75]
	v_mfma_f32_16x16x32_bf16 v[68:71], v[194:197], v[186:189], v[68:71]
	v_mfma_f32_16x16x32_bf16 v[64:67], v[202:205], v[186:189], v[64:67]
	v_mfma_f32_16x16x32_bf16 v[108:111], v[198:201], v[162:165], v[108:111]
	v_mfma_f32_16x16x32_bf16 v[104:107], v[206:209], v[162:165], v[104:107]
	v_mfma_f32_16x16x32_bf16 v[92:95], v[198:201], v[170:173], v[92:95]
	v_mfma_f32_16x16x32_bf16 v[88:91], v[206:209], v[170:173], v[88:91]
	v_mfma_f32_16x16x32_bf16 v[76:79], v[198:201], v[182:185], v[76:79]
	v_mfma_f32_16x16x32_bf16 v[72:75], v[206:209], v[182:185], v[72:75]
	v_mfma_f32_16x16x32_bf16 v[68:71], v[198:201], v[190:193], v[68:71]
	v_mfma_f32_16x16x32_bf16 v[64:67], v[206:209], v[190:193], v[64:67]
	s_mov_b32 m0, s27
	s_barrier
	ds_read_b128 v[158:161], v141 offset:49152
	ds_read_b128 v[162:165], v141 offset:50176
	ds_read_b128 v[166:169], v141 offset:51200
	ds_read_b128 v[170:173], v141 offset:52224
	ds_read_b128 v[178:181], v141 offset:53248
	ds_read_b128 v[182:185], v141 offset:54272
	ds_read_b128 v[186:189], v141 offset:55296
	ds_read_b128 v[190:193], v141 offset:56320
	global_load_lds_dwordx4 v132, s[100:101]
	s_mov_b32 m0, s28
	s_nop 0
	global_load_lds_dwordx4 v130, s[100:101]
	s_barrier
; #define PG8_STAGE(bufoff, gbase, voff) do { _Pragma("unroll") for (int _i = 0; _i < 2; ++_i) \
;         __builtin_amdgcn_global_load_lds((const unsigned*)((const char*)(gbase) + (voff)[_i]), (PG8_LAS unsigned*)(lds + (bufoff) + ldsw + _i * 8192), 16, 0, 0); } while (0)
; #define PG8_LDA(dst, b, h) do { _Pragma("unroll") for (int m = 0; m < 4; ++m) _Pragma("unroll") for (int k = 0; k < 2; ++k) dst[m][k] = *(const PG8_LAS bf16x8*)(lds + PG8_SA(b, h) + aoff + m * 2048 + k * 1024); } while (0)
; #define PG8_MMA(ai, bj, At, Bt) do { __builtin_amdgcn_s_setprio(1); _Pragma("unroll") for (int m = 0; m < 4; ++m) _Pragma("unroll") for (int n = 0; n < 2; ++n) _Pragma("unroll") for (int k = 0; k < 2; ++k) \
;         acc[ai][bj][m][n] = __builtin_amdgcn_mfma_f32_16x16x32_bf16(Bt[n][k], At[m][k], acc[ai][bj][m][n], 0, 0, 0); __builtin_amdgcn_s_setprio(0); } while (0)
; #define PG8_WAIT_V(n) asm volatile("s_waitcnt vmcnt(" #n ")" ::: "memory")
; #define PG8_WAIT_L(n) asm volatile("s_waitcnt lgkmcnt(" #n ")" ::: "memory")
; #define PG8_BAR __builtin_amdgcn_s_barrier()
; #define PG8_SCHED __builtin_amdgcn_sched_barrier(0)
; template <class Epi, class Sched>
; __device__ __forceinline__ void gemm_phase(PG8_LAS unsigned char* lds, const Gemm g, const Sched& S, const Epi& E) {
;     ...
;             PG8_LDA(At, 1, 1); PG8_STAGE(PG8_SA(1, 0), a3, voffA);
;             PG8_BAR; PG8_WAIT_L(0); PG8_MMA(1, 0, At, B0); PG8_BAR; PG8_SCHED;
;             PG8_STAGE(PG8_SB(1, 1), b3 + hstep, voffB);
;             PG8_WAIT_V(6); PG8_BAR; PG8_MMA(1, 1, At, B1); PG8_BAR;
;         }
	s_waitcnt lgkmcnt(0)
	v_mfma_f32_16x16x32_bf16 v[60:63], v[142:145], v[158:161], v[60:63]
	v_mfma_f32_16x16x32_bf16 v[56:59], v[150:153], v[158:161], v[56:59]
	v_mfma_f32_16x16x32_bf16 v[52:55], v[142:145], v[166:169], v[52:55]
	v_mfma_f32_16x16x32_bf16 v[48:51], v[150:153], v[166:169], v[48:51]
	v_mfma_f32_16x16x32_bf16 v[36:39], v[142:145], v[178:181], v[36:39]
	v_mfma_f32_16x16x32_bf16 v[32:35], v[150:153], v[178:181], v[32:35]
	v_mfma_f32_16x16x32_bf16 v[20:23], v[142:145], v[186:189], v[20:23]
	v_mfma_f32_16x16x32_bf16 v[16:19], v[150:153], v[186:189], v[16:19]
	v_mfma_f32_16x16x32_bf16 v[60:63], v[146:149], v[162:165], v[60:63]
	v_mfma_f32_16x16x32_bf16 v[56:59], v[154:157], v[162:165], v[56:59]
	v_mfma_f32_16x16x32_bf16 v[52:55], v[146:149], v[170:173], v[52:55]
	v_mfma_f32_16x16x32_bf16 v[48:51], v[154:157], v[170:173], v[48:51]
	v_mfma_f32_16x16x32_bf16 v[36:39], v[146:149], v[182:185], v[36:39]
	v_mfma_f32_16x16x32_bf16 v[32:35], v[154:157], v[182:185], v[32:35]
	v_mfma_f32_16x16x32_bf16 v[20:23], v[146:149], v[190:193], v[20:23]
	v_mfma_f32_16x16x32_bf16 v[16:19], v[154:157], v[190:193], v[16:19]
	s_barrier
	s_add_u32 s8, s12, 0xb0080
	s_addc_u32 s9, s13, 0
	s_add_i32 s12, s14, s18
	s_mov_b32 m0, s12
	s_nop 0
	global_load_lds_dwordx4 v176, s[8:9]
	s_add_i32 m0, s12, 0x2000
	s_nop 0
	global_load_lds_dwordx4 v128, s[8:9]
	s_waitcnt vmcnt(6)
	s_barrier
	v_mfma_f32_16x16x32_bf16 v[44:47], v[194:197], v[158:161], v[44:47]
	v_mfma_f32_16x16x32_bf16 v[40:43], v[202:205], v[158:161], v[40:43]
	v_mfma_f32_16x16x32_bf16 v[28:31], v[194:197], v[166:169], v[28:31]
	v_mfma_f32_16x16x32_bf16 v[24:27], v[202:205], v[166:169], v[24:27]
	v_mfma_f32_16x16x32_bf16 v[12:15], v[194:197], v[178:181], v[12:15]
	v_mfma_f32_16x16x32_bf16 v[8:11], v[202:205], v[178:181], v[8:11]
	v_mfma_f32_16x16x32_bf16 v[4:7], v[194:197], v[186:189], v[4:7]
	v_mfma_f32_16x16x32_bf16 v[0:3], v[202:205], v[186:189], v[0:3]
	v_mfma_f32_16x16x32_bf16 v[44:47], v[198:201], v[162:165], v[44:47]
	v_mfma_f32_16x16x32_bf16 v[40:43], v[206:209], v[162:165], v[40:43]
	v_mfma_f32_16x16x32_bf16 v[28:31], v[198:201], v[170:173], v[28:31]
	v_mfma_f32_16x16x32_bf16 v[24:27], v[206:209], v[170:173], v[24:27]
	v_mfma_f32_16x16x32_bf16 v[12:15], v[198:201], v[182:185], v[12:15]
	v_mfma_f32_16x16x32_bf16 v[8:11], v[206:209], v[182:185], v[8:11]
	v_mfma_f32_16x16x32_bf16 v[4:7], v[198:201], v[190:193], v[4:7]
	v_mfma_f32_16x16x32_bf16 v[0:3], v[206:209], v[190:193], v[0:3]
	s_add_i32 s45, s45, 2
	s_add_u32 s43, s43, 0x100
	s_addc_u32 s44, s44, 0
	s_cmp_gt_u32 s45, 41
	s_mov_b64 s[8:9], s[10:11]
	s_barrier
	s_cbranch_scc0 .LBB0_96
; __device__ __forceinline__ unsigned cvtpk(float lo, float hi) { const f32x2 v = (f32x2){lo, hi}; const bf16v2 b = __builtin_convertvector(v, bf16v2); return __builtin_bit_cast(unsigned, b); }
; #define PG8_WAIT_V(n) asm volatile("s_waitcnt vmcnt(" #n ")" ::: "memory")
; #define PG8_BAR __builtin_amdgcn_s_barrier()
; template <class Epi, class Sched>
; __device__ __forceinline__ void gemm_phase(PG8_LAS unsigned char* lds, const Gemm g, const Sched& S, const Epi& E) {
;     ...
;         if constexpr (!Epi::AFTER_DRAIN) { E(acc, cur, wr, wc, fr, fq); S.done(cur); }
;         if (!has_next) break;
; #pragma unroll
;         for (int a = 0; a < 2; ++a)
; #pragma unroll
;             for (int b = 0; b < 2; ++b)
; #pragma unroll
;                 for (int m = 0; m < 4; ++m)
; #pragma unroll
;                     for (int n = 0; n < 2; ++n) acc[a][b][m][n] = (f32x4){0.f, 0.f, 0.f, 0.f};
;         cur = nxt; cA = nA; cB = nB; ++ui;
;     }
;     PG8_WAIT_V(0);
;     if (wr == 0) PG8_BAR;
;     PG8_BAR;
;     __device__ __forceinline__ void operator()(const f32x4 (&acc)[2][2][4][2], const pg8::Unit& u, int wr, int wc, int fr, int fq) const {
;         const int row0 = u.pm * 256 + wr * 64 + fr, col0 = u.pn * 256 + wc * 32 + 8 * fq;
; #pragma unroll
;         for (int ai = 0; ai < 2; ++ai)
; #pragma unroll
;             for (int m = 0; m < 4; ++m) { bf16_t* rowp = O + (size_t)(row0 + ai * 128 + m * 16) * ldc + col0;
; #pragma unroll
;                 for (int bj = 0; bj < 2; ++bj) { const f32x4 v0 = acc[ai][bj][m][0], v1 = acc[ai][bj][m][1];
;                     u32x4 w; w.x = cvtpk(v0[0], v0[1]); w.y = cvtpk(v0[2], v0[3]); w.z = cvtpk(v1[0], v1[1]); w.w = cvtpk(v1[2], v1[3]);
;                     *(u32x4*)(rowp + bj * 128) = w; } }
	v_lshl_add_u32 v142, s29, 8, v138
	v_lshl_or_b32 v144, s34, 8, v140
	v_ashrrev_i32_e32 v143, 31, v142
	v_readlane_b32 s8, v253, 18
	v_cvt_pk_bf16_f32 v108, v108, v109
	v_cvt_pk_bf16_f32 v109, v110, v111
	v_cvt_pk_bf16_f32 v110, v104, v105
	v_or_b32_e32 v104, 16, v142
	v_cvt_pk_bf16_f32 v92, v92, v93
	v_cvt_pk_bf16_f32 v93, v94, v95
	v_cvt_pk_bf16_f32 v94, v88, v89
	v_or_b32_e32 v88, 32, v142
	v_cvt_pk_bf16_f32 v76, v76, v77
	v_cvt_pk_bf16_f32 v77, v78, v79
	v_cvt_pk_bf16_f32 v78, v72, v73
	v_or_b32_e32 v72, 48, v142
	v_ashrrev_i32_e32 v145, 31, v144
	v_lshlrev_b64 v[146:147], 11, v[142:143]
	v_readlane_b32 s9, v253, 19
	v_ashrrev_i32_e32 v105, 31, v104
	v_ashrrev_i32_e32 v89, 31, v88
	v_ashrrev_i32_e32 v73, 31, v72
	v_lshl_add_u64 v[146:147], s[8:9], 0, v[146:147]
	v_lshlrev_b64 v[144:145], 1, v[144:145]
	v_lshlrev_b64 v[104:105], 11, v[104:105]
	v_lshlrev_b64 v[88:89], 11, v[88:89]
	v_lshlrev_b64 v[72:73], 11, v[72:73]
	v_lshl_add_u64 v[146:147], v[146:147], 0, v[144:145]
	v_lshl_add_u64 v[104:105], s[8:9], 0, v[104:105]
	v_lshl_add_u64 v[88:89], s[8:9], 0, v[88:89]
	v_lshl_add_u64 v[72:73], s[8:9], 0, v[72:73]
	s_mov_b64 s[8:9], 0x40000
	v_cvt_pk_bf16_f32 v68, v68, v69
	v_cvt_pk_bf16_f32 v69, v70, v71
	v_cvt_pk_bf16_f32 v70, v64, v65
	v_lshl_add_u64 v[64:65], v[146:147], 0, s[8:9]
	v_cvt_pk_bf16_f32 v60, v60, v61
	v_cvt_pk_bf16_f32 v61, v62, v63
	v_cvt_pk_bf16_f32 v62, v56, v57
	v_add_co_u32_e32 v56, vcc, s2, v146
	v_cvt_pk_bf16_f32 v44, v44, v45
	v_cvt_pk_bf16_f32 v45, v46, v47
	v_cvt_pk_bf16_f32 v46, v40, v41
	v_cvt_pk_bf16_f32 v47, v42, v43
	s_mov_b64 s[8:9], 0x48000
	v_addc_co_u32_e32 v57, vcc, 0, v147, vcc
	global_store_dwordx4 v[64:65], v[44:47], off offset:256
	v_cvt_pk_bf16_f32 v28, v28, v29
	v_cvt_pk_bf16_f32 v29, v30, v31
	v_lshl_add_u64 v[44:45], v[146:147], 0, s[8:9]
	s_mov_b32 s8, 0x48000
	v_add_co_u32_e32 v46, vcc, s8, v146
	v_cvt_pk_bf16_f32 v30, v24, v25
	v_cvt_pk_bf16_f32 v31, v26, v27
	s_mov_b64 s[8:9], 0x50000
	v_addc_co_u32_e32 v47, vcc, 0, v147, vcc
	global_store_dwordx4 v[44:45], v[28:31], off offset:256
	v_cvt_pk_bf16_f32 v12, v12, v13
	v_cvt_pk_bf16_f32 v13, v14, v15
	v_lshl_add_u64 v[28:29], v[146:147], 0, s[8:9]
	s_mov_b32 s8, 0x50000
	v_add_co_u32_e32 v30, vcc, s8, v146
	v_cvt_pk_bf16_f32 v14, v8, v9
	v_cvt_pk_bf16_f32 v15, v10, v11
	s_mov_b64 s[8:9], 0x58000
	v_cvt_pk_bf16_f32 v111, v106, v107
	v_addc_co_u32_e32 v31, vcc, 0, v147, vcc
	global_store_dwordx4 v[28:29], v[12:15], off offset:256
	global_store_dwordx4 v[146:147], v[108:111], off offset:256
	v_cvt_pk_bf16_f32 v95, v90, v91
	v_lshl_add_u64 v[12:13], v[146:147], 0, s[8:9]
	s_mov_b32 s8, 0x58000
	v_lshl_add_u64 v[108:109], v[104:105], 0, v[144:145]
	v_add_co_u32_e32 v14, vcc, s8, v146
	global_store_dwordx4 v[108:109], v[92:95], off offset:256
	v_cvt_pk_bf16_f32 v79, v74, v75
	v_addc_co_u32_e32 v15, vcc, 0, v147, vcc
	v_lshl_add_u64 v[92:93], v[88:89], 0, v[144:145]
	v_cvt_pk_bf16_f32 v124, v124, v125
	v_cvt_pk_bf16_f32 v125, v126, v127
	v_cvt_pk_bf16_f32 v126, v120, v121
	v_cvt_pk_bf16_f32 v127, v122, v123
	v_cvt_pk_bf16_f32 v104, v116, v117
	v_cvt_pk_bf16_f32 v105, v118, v119
	v_cvt_pk_bf16_f32 v106, v112, v113
	v_cvt_pk_bf16_f32 v107, v114, v115
	v_cvt_pk_bf16_f32 v88, v100, v101
	v_cvt_pk_bf16_f32 v89, v102, v103
	v_cvt_pk_bf16_f32 v90, v96, v97
	v_cvt_pk_bf16_f32 v91, v98, v99
	global_store_dwordx4 v[92:93], v[76:79], off offset:256
	v_cvt_pk_bf16_f32 v74, v80, v81
	v_cvt_pk_bf16_f32 v75, v82, v83
	v_lshl_add_u64 v[76:77], v[72:73], 0, v[144:145]
	v_cvt_pk_bf16_f32 v72, v84, v85
	v_cvt_pk_bf16_f32 v73, v86, v87
	v_cvt_pk_bf16_f32 v71, v66, v67
	v_cvt_pk_bf16_f32 v63, v58, v59
	v_cvt_pk_bf16_f32 v40, v52, v53
	v_cvt_pk_bf16_f32 v41, v54, v55
	v_cvt_pk_bf16_f32 v42, v48, v49
	v_cvt_pk_bf16_f32 v43, v50, v51
	v_cvt_pk_bf16_f32 v24, v36, v37
	v_cvt_pk_bf16_f32 v25, v38, v39
	v_cvt_pk_bf16_f32 v26, v32, v33
	v_cvt_pk_bf16_f32 v27, v34, v35
	v_cvt_pk_bf16_f32 v8, v20, v21
	v_cvt_pk_bf16_f32 v9, v22, v23
	v_cvt_pk_bf16_f32 v10, v16, v17
	v_cvt_pk_bf16_f32 v11, v18, v19
	v_cvt_pk_bf16_f32 v4, v4, v5
	v_cvt_pk_bf16_f32 v5, v6, v7
	v_cvt_pk_bf16_f32 v6, v0, v1
	v_cvt_pk_bf16_f32 v7, v2, v3
	s_and_b64 vcc, exec, s[38:39]
	s_mov_b32 s34, s40
	s_mov_b32 s29, s41
	s_mov_b64 s[10:11], s[4:5]
	s_mov_b64 s[8:9], s[0:1]
	global_store_dwordx4 v[146:147], v[124:127], off
	global_store_dwordx4 v[108:109], v[104:107], off
	global_store_dwordx4 v[92:93], v[88:91], off
	global_store_dwordx4 v[76:77], v[72:75], off
	global_store_dwordx4 v[76:77], v[68:71], off offset:256
	global_store_dwordx4 v[56:57], v[60:63], off
	global_store_dwordx4 v[46:47], v[40:43], off
	global_store_dwordx4 v[30:31], v[24:27], off
	global_store_dwordx4 v[14:15], v[8:11], off
	global_store_dwordx4 v[12:13], v[4:7], off offset:256
	s_cbranch_vccz .LBB0_89
	s_waitcnt vmcnt(0)
	s_cmpk_gt_u32 s17, 0xff
	v_readlane_b32 s2, v254, 59
	s_cbranch_scc1 .LBB0_100
	s_barrier

; #define PG8_STAGE(bufoff, gbase, voff) do { _Pragma("unroll") for (int _i = 0; _i < 2; ++_i) \
;         __builtin_amdgcn_global_load_lds((const unsigned*)((const char*)(gbase) + (voff)[_i]), (PG8_LAS unsigned*)(lds + (bufoff) + ldsw + _i * 8192), 16, 0, 0); } while (0)
; #define PG8_LDA(dst, b, h) do { _Pragma("unroll") for (int m = 0; m < 4; ++m) _Pragma("unroll") for (int k = 0; k < 2; ++k) dst[m][k] = *(const PG8_LAS bf16x8*)(lds + PG8_SA(b, h) + aoff + m * 2048 + k * 1024); } while (0)
; #define PG8_LDB(dst, b, h) do { _Pragma("unroll") for (int n = 0; n < 2; ++n) _Pragma("unroll") for (int k = 0; k < 2; ++k) dst[n][k] = *(const PG8_LAS bf16x8*)(lds + PG8_SB(b, h) + boff + n * 2048 + k * 1024); } while (0)
; #define PG8_WAIT_V(n) asm volatile("s_waitcnt vmcnt(" #n ")" ::: "memory")
; #define PG8_WAIT_L(n) asm volatile("s_waitcnt lgkmcnt(" #n ")" ::: "memory")
; #define PG8_BAR __builtin_amdgcn_s_barrier()
; #define PG8_SCHED __builtin_amdgcn_sched_barrier(0)
; template <class Epi, class Sched>
; __device__ __forceinline__ void gemm_phase(PG8_LAS unsigned char* lds, const Gemm g, const Sched& S, const Epi& E) {
;     ...
;         const bool has_next = S.next(ui + 1, nxt);
;         const char* nA = has_next ? (const char*)g.A + (size_t)nxt.pm * tstep : cA; const char* nB = has_next ? (const char*)g.Bt + (size_t)nxt.pn * tstep : cB;
;         for (int t = 0; t < nt; t += 2) {
;             const bool last = (t == nt - 2);
;             const char* a1 = cA + (size_t)(t + 1) * kstep;
;             const char* a2 = last ? nA : cA + (size_t)(t + 2) * kstep; const char* b2 = last ? nB : cB + (size_t)(t + 2) * kstep;
;             const char* a3 = a2 + kstep; const char* b3 = b2 + kstep;
;             if (last && has_next) S.a_ready(nxt);
;             PG8_LDB(B0, 0, 0); PG8_SCHED; PG8_LDA(At, 0, 0); PG8_STAGE(PG8_SA(1, 1), a1 + hstep, voffA);
;             PG8_WAIT_L(8); PG8_BAR; PG8_WAIT_L(0); PG8_MMA(0, 0, At, B0); PG8_BAR; PG8_SCHED;
;             PG8_LDB(B1, 0, 1); PG8_STAGE(PG8_SB(0, 0), b2, voffB);
;             PG8_BAR; PG8_WAIT_L(0); PG8_MMA(0, 1, At, B1); PG8_BAR;
;             PG8_LDA(At, 0, 1); PG8_STAGE(PG8_SA(0, 0), a2, voffA);
;             PG8_BAR; PG8_WAIT_L(0); PG8_MMA(1, 0, At, B0); PG8_BAR; PG8_SCHED;
;             PG8_STAGE(PG8_SB(0, 1), b2 + hstep, voffB);
;             PG8_WAIT_V(6); PG8_BAR; PG8_MMA(1, 1, At, B1); PG8_BAR;
.LBB0_114:
	s_add_u32 s14, s12, 0xfffc0080
	s_addc_u32 s15, s13, -1
	s_add_i32 s46, 0, 0x10000
	v_add_u32_e32 v154, s46, v143
	ds_read_b128 v[138:141], v154
	ds_read_b128 v[146:149], v154 offset:1024
	ds_read_b128 v[150:153], v154 offset:2048
	ds_read_b128 v[154:157], v154 offset:3072
	s_cmp_eq_u32 s45, 12
	s_cselect_b32 s17, s5, s15
	s_cselect_b32 s16, s40, s14
	s_cselect_b32 s15, s1, s44
	s_cselect_b32 s14, s41, s43
	s_add_i32 m0, s11, 0xc000
	ds_read_b128 v[158:161], v145
	ds_read_b128 v[162:165], v145 offset:1024
	ds_read_b128 v[166:169], v145 offset:2048
	ds_read_b128 v[170:173], v145 offset:3072
	ds_read_b128 v[178:181], v145 offset:4096
	ds_read_b128 v[182:185], v145 offset:5120
	ds_read_b128 v[186:189], v145 offset:6144
	ds_read_b128 v[190:193], v145 offset:7168
	global_load_lds_dwordx4 v134, s[12:13]
	s_add_i32 m0, s11, 0xe000
	s_nop 0
	global_load_lds_dwordx4 v136, s[12:13]
	s_waitcnt lgkmcnt(8)
	s_barrier
	s_waitcnt lgkmcnt(0)
	v_mfma_f32_16x16x32_bf16 v[124:127], v[138:141], v[158:161], v[124:127]
	v_mfma_f32_16x16x32_bf16 v[116:119], v[150:153], v[158:161], v[116:119]
	v_mfma_f32_16x16x32_bf16 v[108:111], v[138:141], v[166:169], v[108:111]
	v_mfma_f32_16x16x32_bf16 v[100:103], v[150:153], v[166:169], v[100:103]
	v_mfma_f32_16x16x32_bf16 v[92:95], v[138:141], v[178:181], v[92:95]
	v_mfma_f32_16x16x32_bf16 v[84:87], v[150:153], v[178:181], v[84:87]
	v_mfma_f32_16x16x32_bf16 v[76:79], v[138:141], v[186:189], v[76:79]
	v_mfma_f32_16x16x32_bf16 v[68:71], v[150:153], v[186:189], v[68:71]
	v_mfma_f32_16x16x32_bf16 v[124:127], v[146:149], v[162:165], v[124:127]
	v_mfma_f32_16x16x32_bf16 v[116:119], v[154:157], v[162:165], v[116:119]
	v_mfma_f32_16x16x32_bf16 v[108:111], v[146:149], v[170:173], v[108:111]
	v_mfma_f32_16x16x32_bf16 v[100:103], v[154:157], v[170:173], v[100:103]
	v_mfma_f32_16x16x32_bf16 v[92:95], v[146:149], v[182:185], v[92:95]
	v_mfma_f32_16x16x32_bf16 v[84:87], v[154:157], v[182:185], v[84:87]
	v_mfma_f32_16x16x32_bf16 v[76:79], v[146:149], v[190:193], v[76:79]
	v_mfma_f32_16x16x32_bf16 v[68:71], v[154:157], v[190:193], v[68:71]
	s_barrier
	s_add_i32 s48, 0, 0x14000
	v_add_u32_e32 v174, s48, v143
	s_add_i32 s46, s46, s20
	ds_read_b128 v[194:197], v174
	ds_read_b128 v[198:201], v174 offset:1024
	ds_read_b128 v[202:205], v174 offset:2048
	ds_read_b128 v[206:209], v174 offset:3072
	s_add_u32 s98, s14, 0x80
	s_addc_u32 s99, s15, 0
	s_mov_b32 m0, s46
	s_nop 0
	global_load_lds_dwordx4 v176, s[14:15]
	s_add_i32 m0, s46, 0x2000
	s_nop 0
	global_load_lds_dwordx4 v128, s[14:15]
	s_barrier
	s_waitcnt lgkmcnt(0)
	v_mfma_f32_16x16x32_bf16 v[120:123], v[194:197], v[158:161], v[120:123]
	v_mfma_f32_16x16x32_bf16 v[112:115], v[202:205], v[158:161], v[112:115]
	v_mfma_f32_16x16x32_bf16 v[104:107], v[194:197], v[166:169], v[104:107]
	v_mfma_f32_16x16x32_bf16 v[96:99], v[202:205], v[166:169], v[96:99]
	v_mfma_f32_16x16x32_bf16 v[88:91], v[194:197], v[178:181], v[88:91]
	v_mfma_f32_16x16x32_bf16 v[80:83], v[202:205], v[178:181], v[80:83]
	v_mfma_f32_16x16x32_bf16 v[72:75], v[194:197], v[186:189], v[72:75]
	v_mfma_f32_16x16x32_bf16 v[64:67], v[202:205], v[186:189], v[64:67]
	v_mfma_f32_16x16x32_bf16 v[120:123], v[198:201], v[162:165], v[120:123]
	v_mfma_f32_16x16x32_bf16 v[112:115], v[206:209], v[162:165], v[112:115]
	v_mfma_f32_16x16x32_bf16 v[104:107], v[198:201], v[170:173], v[104:107]
	v_mfma_f32_16x16x32_bf16 v[96:99], v[206:209], v[170:173], v[96:99]
	v_mfma_f32_16x16x32_bf16 v[88:91], v[198:201], v[182:185], v[88:91]
	v_mfma_f32_16x16x32_bf16 v[80:83], v[206:209], v[182:185], v[80:83]
	v_mfma_f32_16x16x32_bf16 v[72:75], v[198:201], v[190:193], v[72:75]
	v_mfma_f32_16x16x32_bf16 v[64:67], v[206:209], v[190:193], v[64:67]
	s_mov_b32 m0, s11
	s_add_u32 s100, s16, 0x80
	s_addc_u32 s101, s17, 0
	s_barrier
	ds_read_b128 v[158:161], v145 offset:16384
	ds_read_b128 v[162:165], v145 offset:17408
	ds_read_b128 v[166:169], v145 offset:18432
	ds_read_b128 v[170:173], v145 offset:19456
	ds_read_b128 v[178:181], v145 offset:20480
	ds_read_b128 v[182:185], v145 offset:21504
	ds_read_b128 v[186:189], v145 offset:22528
	ds_read_b128 v[190:193], v145 offset:23552
	global_load_lds_dwordx4 v132, s[16:17]
	s_mov_b32 m0, s22
	s_nop 0
	global_load_lds_dwordx4 v130, s[16:17]
	s_barrier
	s_waitcnt lgkmcnt(0)
	v_mfma_f32_16x16x32_bf16 v[60:63], v[138:141], v[158:161], v[60:63]
	v_mfma_f32_16x16x32_bf16 v[52:55], v[150:153], v[158:161], v[52:55]
	v_mfma_f32_16x16x32_bf16 v[44:47], v[138:141], v[166:169], v[44:47]
	v_mfma_f32_16x16x32_bf16 v[36:39], v[150:153], v[166:169], v[36:39]
	v_mfma_f32_16x16x32_bf16 v[28:31], v[138:141], v[178:181], v[28:31]
	v_mfma_f32_16x16x32_bf16 v[20:23], v[150:153], v[178:181], v[20:23]
	v_mfma_f32_16x16x32_bf16 v[12:15], v[138:141], v[186:189], v[12:15]
	v_mfma_f32_16x16x32_bf16 v[4:7], v[150:153], v[186:189], v[4:7]
	v_mfma_f32_16x16x32_bf16 v[60:63], v[146:149], v[162:165], v[60:63]
	v_mfma_f32_16x16x32_bf16 v[52:55], v[154:157], v[162:165], v[52:55]
	v_mfma_f32_16x16x32_bf16 v[44:47], v[146:149], v[170:173], v[44:47]
	v_mfma_f32_16x16x32_bf16 v[36:39], v[154:157], v[170:173], v[36:39]
	v_mfma_f32_16x16x32_bf16 v[28:31], v[146:149], v[182:185], v[28:31]
	v_mfma_f32_16x16x32_bf16 v[20:23], v[154:157], v[182:185], v[20:23]
	v_mfma_f32_16x16x32_bf16 v[12:15], v[146:149], v[190:193], v[12:15]
	v_mfma_f32_16x16x32_bf16 v[4:7], v[154:157], v[190:193], v[4:7]
	s_barrier
	s_add_u32 s46, s14, 0x40000
	s_addc_u32 s47, s15, 0
	s_add_i32 s48, s48, s20
	s_mov_b32 m0, s48
	s_nop 0
	global_load_lds_dwordx4 v176, s[46:47]
	s_add_i32 m0, s48, 0x2000
	s_nop 0
	global_load_lds_dwordx4 v128, s[46:47]
	s_waitcnt vmcnt(6)
	s_barrier
; #define PG8_STAGE(bufoff, gbase, voff) do { _Pragma("unroll") for (int _i = 0; _i < 2; ++_i) \
;         __builtin_amdgcn_global_load_lds((const unsigned*)((const char*)(gbase) + (voff)[_i]), (PG8_LAS unsigned*)(lds + (bufoff) + ldsw + _i * 8192), 16, 0, 0); } while (0)
; #define PG8_LDA(dst, b, h) do { _Pragma("unroll") for (int m = 0; m < 4; ++m) _Pragma("unroll") for (int k = 0; k < 2; ++k) dst[m][k] = *(const PG8_LAS bf16x8*)(lds + PG8_SA(b, h) + aoff + m * 2048 + k * 1024); } while (0)
; #define PG8_LDB(dst, b, h) do { _Pragma("unroll") for (int n = 0; n < 2; ++n) _Pragma("unroll") for (int k = 0; k < 2; ++k) dst[n][k] = *(const PG8_LAS bf16x8*)(lds + PG8_SB(b, h) + boff + n * 2048 + k * 1024); } while (0)
; #define PG8_MMA(ai, bj, At, Bt) do { __builtin_amdgcn_s_setprio(1); _Pragma("unroll") for (int m = 0; m < 4; ++m) _Pragma("unroll") for (int n = 0; n < 2; ++n) _Pragma("unroll") for (int k = 0; k < 2; ++k) \
;         acc[ai][bj][m][n] = __builtin_amdgcn_mfma_f32_16x16x32_bf16(Bt[n][k], At[m][k], acc[ai][bj][m][n], 0, 0, 0); __builtin_amdgcn_s_setprio(0); } while (0)
; #define PG8_WAIT_V(n) asm volatile("s_waitcnt vmcnt(" #n ")" ::: "memory")
; #define PG8_WAIT_L(n) asm volatile("s_waitcnt lgkmcnt(" #n ")" ::: "memory")
; #define PG8_BAR __builtin_amdgcn_s_barrier()
; #define PG8_SCHED __builtin_amdgcn_sched_barrier(0)
; template <class Epi, class Sched>
; __device__ __forceinline__ void gemm_phase(PG8_LAS unsigned char* lds, const Gemm g, const Sched& S, const Epi& E) {
;     ...
;             PG8_WAIT_V(6); PG8_BAR; PG8_MMA(1, 1, At, B1); PG8_BAR;
;             PG8_LDB(B0, 1, 0); PG8_SCHED; PG8_LDA(At, 1, 0); PG8_STAGE(PG8_SA(0, 1), a2 + hstep, voffA);
;             PG8_WAIT_L(8); PG8_BAR; PG8_WAIT_L(0); PG8_MMA(0, 0, At, B0); PG8_BAR; PG8_SCHED;
;             PG8_LDB(B1, 1, 1); PG8_STAGE(PG8_SB(1, 0), b3, voffB);
;             PG8_BAR; PG8_WAIT_L(0); PG8_MMA(0, 1, At, B1); PG8_BAR;
;             PG8_LDA(At, 1, 1); PG8_STAGE(PG8_SA(1, 0), a3, voffA);
	v_mfma_f32_16x16x32_bf16 v[56:59], v[194:197], v[158:161], v[56:59]
	v_mfma_f32_16x16x32_bf16 v[48:51], v[202:205], v[158:161], v[48:51]
	v_mfma_f32_16x16x32_bf16 v[40:43], v[194:197], v[166:169], v[40:43]
	v_mfma_f32_16x16x32_bf16 v[32:35], v[202:205], v[166:169], v[32:35]
	v_mfma_f32_16x16x32_bf16 v[24:27], v[194:197], v[178:181], v[24:27]
	v_mfma_f32_16x16x32_bf16 v[16:19], v[202:205], v[178:181], v[16:19]
	v_mfma_f32_16x16x32_bf16 v[8:11], v[194:197], v[186:189], v[8:11]
	v_mfma_f32_16x16x32_bf16 v[0:3], v[202:205], v[186:189], v[0:3]
	v_mfma_f32_16x16x32_bf16 v[56:59], v[198:201], v[162:165], v[56:59]
	v_mfma_f32_16x16x32_bf16 v[48:51], v[206:209], v[162:165], v[48:51]
	v_mfma_f32_16x16x32_bf16 v[40:43], v[198:201], v[170:173], v[40:43]
	v_mfma_f32_16x16x32_bf16 v[32:35], v[206:209], v[170:173], v[32:35]
	v_mfma_f32_16x16x32_bf16 v[24:27], v[198:201], v[182:185], v[24:27]
	v_mfma_f32_16x16x32_bf16 v[16:19], v[206:209], v[182:185], v[16:19]
	v_mfma_f32_16x16x32_bf16 v[8:11], v[198:201], v[190:193], v[8:11]
	v_mfma_f32_16x16x32_bf16 v[0:3], v[206:209], v[190:193], v[0:3]
	s_add_i32 s46, 0, 0x18000
	v_add_u32_e32 v154, s46, v143
	s_barrier
	ds_read_b128 v[138:141], v154
	ds_read_b128 v[146:149], v154 offset:1024
	ds_read_b128 v[150:153], v154 offset:2048
	ds_read_b128 v[154:157], v154 offset:3072
	s_add_u32 s16, s16, 0x40000
	s_addc_u32 s17, s17, 0
	s_mov_b32 m0, s23
	ds_read_b128 v[158:161], v145 offset:32768
	ds_read_b128 v[162:165], v145 offset:33792
	ds_read_b128 v[166:169], v145 offset:34816
	ds_read_b128 v[170:173], v145 offset:35840
	ds_read_b128 v[178:181], v145 offset:36864
	ds_read_b128 v[182:185], v145 offset:37888
	ds_read_b128 v[186:189], v145 offset:38912
	ds_read_b128 v[190:193], v145 offset:39936
	global_load_lds_dwordx4 v132, s[16:17]
	s_mov_b32 m0, s26
	s_nop 0
	global_load_lds_dwordx4 v130, s[16:17]
	s_waitcnt lgkmcnt(8)
	s_barrier
	s_waitcnt lgkmcnt(0)
	v_mfma_f32_16x16x32_bf16 v[124:127], v[138:141], v[158:161], v[124:127]
	v_mfma_f32_16x16x32_bf16 v[116:119], v[150:153], v[158:161], v[116:119]
	v_mfma_f32_16x16x32_bf16 v[108:111], v[138:141], v[166:169], v[108:111]
	v_mfma_f32_16x16x32_bf16 v[100:103], v[150:153], v[166:169], v[100:103]
	v_mfma_f32_16x16x32_bf16 v[92:95], v[138:141], v[178:181], v[92:95]
	v_mfma_f32_16x16x32_bf16 v[84:87], v[150:153], v[178:181], v[84:87]
	v_mfma_f32_16x16x32_bf16 v[76:79], v[138:141], v[186:189], v[76:79]
	v_mfma_f32_16x16x32_bf16 v[68:71], v[150:153], v[186:189], v[68:71]
	v_mfma_f32_16x16x32_bf16 v[124:127], v[146:149], v[162:165], v[124:127]
	v_mfma_f32_16x16x32_bf16 v[116:119], v[154:157], v[162:165], v[116:119]
	v_mfma_f32_16x16x32_bf16 v[108:111], v[146:149], v[170:173], v[108:111]
	v_mfma_f32_16x16x32_bf16 v[100:103], v[154:157], v[170:173], v[100:103]
	v_mfma_f32_16x16x32_bf16 v[92:95], v[146:149], v[182:185], v[92:95]
	v_mfma_f32_16x16x32_bf16 v[84:87], v[154:157], v[182:185], v[84:87]
	v_mfma_f32_16x16x32_bf16 v[76:79], v[146:149], v[190:193], v[76:79]
	v_mfma_f32_16x16x32_bf16 v[68:71], v[154:157], v[190:193], v[68:71]
	s_barrier
	s_add_i32 s16, 0, 0x1c000
	s_add_i32 s17, s46, s20
	v_add_u32_e32 v206, s16, v143
	s_mov_b32 m0, s17
	ds_read_b128 v[194:197], v206
	ds_read_b128 v[198:201], v206 offset:1024
	ds_read_b128 v[202:205], v206 offset:2048
	ds_read_b128 v[206:209], v206 offset:3072
	global_load_lds_dwordx4 v176, s[98:99]
	s_add_i32 m0, s17, 0x2000
	s_nop 0
	global_load_lds_dwordx4 v128, s[98:99]
	s_barrier
	s_waitcnt lgkmcnt(0)
	v_mfma_f32_16x16x32_bf16 v[120:123], v[194:197], v[158:161], v[120:123]
	v_mfma_f32_16x16x32_bf16 v[112:115], v[202:205], v[158:161], v[112:115]
	v_mfma_f32_16x16x32_bf16 v[104:107], v[194:197], v[166:169], v[104:107]
	v_mfma_f32_16x16x32_bf16 v[96:99], v[202:205], v[166:169], v[96:99]
	v_mfma_f32_16x16x32_bf16 v[88:91], v[194:197], v[178:181], v[88:91]
	v_mfma_f32_16x16x32_bf16 v[80:83], v[202:205], v[178:181], v[80:83]
	v_mfma_f32_16x16x32_bf16 v[72:75], v[194:197], v[186:189], v[72:75]
	v_mfma_f32_16x16x32_bf16 v[64:67], v[202:205], v[186:189], v[64:67]
	v_mfma_f32_16x16x32_bf16 v[120:123], v[198:201], v[162:165], v[120:123]
	v_mfma_f32_16x16x32_bf16 v[112:115], v[206:209], v[162:165], v[112:115]
	v_mfma_f32_16x16x32_bf16 v[104:107], v[198:201], v[170:173], v[104:107]
	v_mfma_f32_16x16x32_bf16 v[96:99], v[206:209], v[170:173], v[96:99]
	v_mfma_f32_16x16x32_bf16 v[88:91], v[198:201], v[182:185], v[88:91]
	v_mfma_f32_16x16x32_bf16 v[80:83], v[206:209], v[182:185], v[80:83]
	v_mfma_f32_16x16x32_bf16 v[72:75], v[198:201], v[190:193], v[72:75]
	v_mfma_f32_16x16x32_bf16 v[64:67], v[206:209], v[190:193], v[64:67]
	s_mov_b32 m0, s28
	s_barrier
	ds_read_b128 v[158:161], v145 offset:49152
	ds_read_b128 v[162:165], v145 offset:50176
	ds_read_b128 v[166:169], v145 offset:51200
	ds_read_b128 v[170:173], v145 offset:52224
	ds_read_b128 v[178:181], v145 offset:53248
	ds_read_b128 v[182:185], v145 offset:54272
	ds_read_b128 v[186:189], v145 offset:55296
	ds_read_b128 v[190:193], v145 offset:56320
	global_load_lds_dwordx4 v132, s[100:101]
	s_mov_b32 m0, s29
	s_nop 0
	global_load_lds_dwordx4 v130, s[100:101]
	s_barrier
; __device__ __forceinline__ unsigned cvtpk(float lo, float hi) { const f32x2 v = (f32x2){lo, hi}; const bf16v2 b = __builtin_convertvector(v, bf16v2); return __builtin_bit_cast(unsigned, b); }
; __device__ __forceinline__ float siluf_(float x) { return x * sigmoidf_(x); }
; #define PG8_STAGE(bufoff, gbase, voff) do { _Pragma("unroll") for (int _i = 0; _i < 2; ++_i) \
;         __builtin_amdgcn_global_load_lds((const unsigned*)((const char*)(gbase) + (voff)[_i]), (PG8_LAS unsigned*)(lds + (bufoff) + ldsw + _i * 8192), 16, 0, 0); } while (0)
; #define PG8_LDA(dst, b, h) do { _Pragma("unroll") for (int m = 0; m < 4; ++m) _Pragma("unroll") for (int k = 0; k < 2; ++k) dst[m][k] = *(const PG8_LAS bf16x8*)(lds + PG8_SA(b, h) + aoff + m * 2048 + k * 1024); } while (0)
; #define PG8_WAIT_V(n) asm volatile("s_waitcnt vmcnt(" #n ")" ::: "memory")
; #define PG8_WAIT_L(n) asm volatile("s_waitcnt lgkmcnt(" #n ")" ::: "memory")
; #define PG8_BAR __builtin_amdgcn_s_barrier()
; #define PG8_SCHED __builtin_amdgcn_sched_barrier(0)
; template <class Epi, class Sched>
; __device__ __forceinline__ void gemm_phase(PG8_LAS unsigned char* lds, const Gemm g, const Sched& S, const Epi& E) {
;     ...
;             PG8_LDA(At, 1, 1); PG8_STAGE(PG8_SA(1, 0), a3, voffA);
;             PG8_BAR; PG8_WAIT_L(0); PG8_MMA(1, 0, At, B0); PG8_BAR; PG8_SCHED;
;             PG8_STAGE(PG8_SB(1, 1), b3 + hstep, voffB);
;             PG8_WAIT_V(6); PG8_BAR; PG8_MMA(1, 1, At, B1); PG8_BAR;
;         }
;     __device__ __forceinline__ void operator()(const f32x4 (&acc)[2][2][4][2], const pg8::Unit& u, int wr, int wc, int fr, int fq) const {
;         const int row0 = u.pm * 256 + wr * 64 + fr, col0 = u.pn * 128 + wc * 32 + 8 * fq;
; #pragma unroll
;         for (int ai = 0; ai < 2; ++ai)
; #pragma unroll
;             for (int m = 0; m < 4; ++m) { bf16_t* rowp = O + (size_t)(row0 + ai * 128 + m * 16) * ldc + col0;
;                 const f32x4 g0 = acc[ai][0][m][0], g1 = acc[ai][0][m][1], u0 = acc[ai][1][m][0], u1 = acc[ai][1][m][1];
;                 u32x4 w; w.x = cvtpk(siluf_(g0[0]) * u0[0], siluf_(g0[1]) * u0[1]); w.y = cvtpk(siluf_(g0[2]) * u0[2], siluf_(g0[3]) * u0[3]);
;                 w.z = cvtpk(siluf_(g1[0]) * u1[0], siluf_(g1[1]) * u1[1]); w.w = cvtpk(siluf_(g1[2]) * u1[2], siluf_(g1[3]) * u1[3]);
;                 *(u32x4*)rowp = w; }
	s_waitcnt lgkmcnt(0)
	v_mfma_f32_16x16x32_bf16 v[60:63], v[138:141], v[158:161], v[60:63]
	v_mfma_f32_16x16x32_bf16 v[52:55], v[150:153], v[158:161], v[52:55]
	v_mfma_f32_16x16x32_bf16 v[44:47], v[138:141], v[166:169], v[44:47]
	v_mfma_f32_16x16x32_bf16 v[36:39], v[150:153], v[166:169], v[36:39]
	v_mfma_f32_16x16x32_bf16 v[28:31], v[138:141], v[178:181], v[28:31]
	v_mfma_f32_16x16x32_bf16 v[20:23], v[150:153], v[178:181], v[20:23]
	v_mfma_f32_16x16x32_bf16 v[12:15], v[138:141], v[186:189], v[12:15]
	v_mfma_f32_16x16x32_bf16 v[4:7], v[150:153], v[186:189], v[4:7]
	v_mfma_f32_16x16x32_bf16 v[60:63], v[146:149], v[162:165], v[60:63]
	v_mfma_f32_16x16x32_bf16 v[52:55], v[154:157], v[162:165], v[52:55]
	v_mfma_f32_16x16x32_bf16 v[44:47], v[146:149], v[170:173], v[44:47]
	v_mfma_f32_16x16x32_bf16 v[36:39], v[154:157], v[170:173], v[36:39]
	v_mfma_f32_16x16x32_bf16 v[28:31], v[146:149], v[182:185], v[28:31]
	v_mfma_f32_16x16x32_bf16 v[20:23], v[154:157], v[182:185], v[20:23]
	v_mfma_f32_16x16x32_bf16 v[12:15], v[146:149], v[190:193], v[12:15]
	v_mfma_f32_16x16x32_bf16 v[4:7], v[154:157], v[190:193], v[4:7]
	s_barrier
	s_add_u32 s14, s14, 0x40080
	s_addc_u32 s15, s15, 0
	s_add_i32 s16, s16, s20
	s_mov_b32 m0, s16
	s_nop 0
	global_load_lds_dwordx4 v176, s[14:15]
	s_add_i32 m0, s16, 0x2000
	s_nop 0
	global_load_lds_dwordx4 v128, s[14:15]
	s_waitcnt vmcnt(6)
	s_barrier
	v_mfma_f32_16x16x32_bf16 v[56:59], v[194:197], v[158:161], v[56:59]
	v_mfma_f32_16x16x32_bf16 v[48:51], v[202:205], v[158:161], v[48:51]
	v_mfma_f32_16x16x32_bf16 v[40:43], v[194:197], v[166:169], v[40:43]
	v_mfma_f32_16x16x32_bf16 v[32:35], v[202:205], v[166:169], v[32:35]
	v_mfma_f32_16x16x32_bf16 v[24:27], v[194:197], v[178:181], v[24:27]
	v_mfma_f32_16x16x32_bf16 v[16:19], v[202:205], v[178:181], v[16:19]
	v_mfma_f32_16x16x32_bf16 v[8:11], v[194:197], v[186:189], v[8:11]
	v_mfma_f32_16x16x32_bf16 v[0:3], v[202:205], v[186:189], v[0:3]
	v_mfma_f32_16x16x32_bf16 v[56:59], v[198:201], v[162:165], v[56:59]
	v_mfma_f32_16x16x32_bf16 v[48:51], v[206:209], v[162:165], v[48:51]
	v_mfma_f32_16x16x32_bf16 v[40:43], v[198:201], v[170:173], v[40:43]
	v_mfma_f32_16x16x32_bf16 v[32:35], v[206:209], v[170:173], v[32:35]
	v_mfma_f32_16x16x32_bf16 v[24:27], v[198:201], v[182:185], v[24:27]
	v_mfma_f32_16x16x32_bf16 v[16:19], v[206:209], v[182:185], v[16:19]
	v_mfma_f32_16x16x32_bf16 v[8:11], v[198:201], v[190:193], v[8:11]
	v_mfma_f32_16x16x32_bf16 v[0:3], v[206:209], v[190:193], v[0:3]
	s_add_i32 s45, s45, 2
	s_add_u32 s12, s12, 0x100
	s_addc_u32 s13, s13, 0
	s_add_u32 s43, s43, 0x100
	s_addc_u32 s44, s44, 0
	s_cmp_gt_u32 s45, 13
	s_barrier
	s_cbranch_scc0 .LBB0_114
	v_mul_f32_e32 v147, 0xbfb8aa3b, v124
	v_exp_f32_e32 v147, v147
	v_readlane_b32 s12, v253, 16
	v_lshl_add_u32 v146, s10, 8, v142
	v_lshl_or_b32 v140, s34, 7, v144
	v_add_f32_e32 v147, 1.0, v147
	v_rcp_f32_e32 v150, v147
	v_mul_f32_e32 v147, 0xbfb8aa3b, v125
	v_exp_f32_e32 v147, v147
	v_readlane_b32 s13, v253, 17
	v_ashrrev_i32_e32 v141, 31, v140
	v_lshlrev_b64 v[140:141], 1, v[140:141]
	v_add_f32_e32 v147, 1.0, v147
	v_rcp_f32_e32 v151, v147
	v_mov_b64_e32 v[138:139], s[12:13]
	v_mad_i64_i32 v[148:149], s[12:13], v146, s81, v[138:139]
	v_pk_mul_f32 v[124:125], v[124:125], v[150:151]
	v_lshl_add_u64 v[148:149], v[148:149], 0, v[140:141]
	v_pk_mul_f32 v[120:121], v[124:125], v[120:121]
	s_and_b64 vcc, exec, s[38:39]
	v_cvt_pk_bf16_f32 v120, v120, v121
	v_mul_f32_e32 v121, 0xbfb8aa3b, v126
	v_exp_f32_e32 v121, v121
	s_mov_b32 s34, s0
	s_mov_b32 s10, s4
	s_mov_b64 s[14:15], s[8:9]
	v_add_f32_e32 v121, 1.0, v121
	v_rcp_f32_e32 v124, v121
	v_mul_f32_e32 v121, 0xbfb8aa3b, v127
	v_exp_f32_e32 v121, v121
	s_nop 0
	v_add_f32_e32 v121, 1.0, v121
	v_rcp_f32_e32 v125, v121
	s_nop 0
	v_pk_mul_f32 v[124:125], v[126:127], v[124:125]
	s_nop 0
	v_pk_mul_f32 v[122:123], v[124:125], v[122:123]
	s_nop 0
	v_cvt_pk_bf16_f32 v121, v122, v123
	v_mul_f32_e32 v122, 0xbfb8aa3b, v116
	v_mul_f32_e32 v123, 0xbfb8aa3b, v117
	v_exp_f32_e32 v122, v122
	v_exp_f32_e32 v123, v123
	v_add_f32_e32 v122, 1.0, v122
	v_add_f32_e32 v123, 1.0, v123
	v_rcp_f32_e32 v122, v122
	v_rcp_f32_e32 v123, v123
	s_nop 0
	v_pk_mul_f32 v[116:117], v[116:117], v[122:123]
	s_nop 0
	v_pk_mul_f32 v[112:113], v[116:117], v[112:113]
	s_nop 0
	v_cvt_pk_bf16_f32 v122, v112, v113
	v_mul_f32_e32 v112, 0xbfb8aa3b, v118
	v_mul_f32_e32 v113, 0xbfb8aa3b, v119
	v_exp_f32_e32 v112, v112
	v_exp_f32_e32 v113, v113
	v_add_f32_e32 v112, 1.0, v112
	v_add_f32_e32 v113, 1.0, v113
	v_rcp_f32_e32 v112, v112
	v_rcp_f32_e32 v113, v113
	s_nop 0
	v_pk_mul_f32 v[112:113], v[118:119], v[112:113]
	s_nop 0
	v_pk_mul_f32 v[112:113], v[112:113], v[114:115]
	v_mul_f32_e32 v114, 0xbfb8aa3b, v108
	v_mul_f32_e32 v115, 0xbfb8aa3b, v109
	v_exp_f32_e32 v114, v114
	v_exp_f32_e32 v115, v115
	v_cvt_pk_bf16_f32 v123, v112, v113
	v_or_b32_e32 v112, 16, v146
	v_add_f32_e32 v114, 1.0, v114
	v_add_f32_e32 v115, 1.0, v115
	v_rcp_f32_e32 v114, v114
	v_rcp_f32_e32 v115, v115
	v_mad_i64_i32 v[112:113], s[12:13], v112, s81, v[138:139]
	v_lshl_add_u64 v[112:113], v[112:113], 0, v[140:141]
	v_pk_mul_f32 v[108:109], v[108:109], v[114:115]
	global_store_dwordx4 v[148:149], v[120:123], off
	v_pk_mul_f32 v[104:105], v[108:109], v[104:105]
	s_nop 0
	v_cvt_pk_bf16_f32 v104, v104, v105
	v_mul_f32_e32 v105, 0xbfb8aa3b, v110
	v_exp_f32_e32 v105, v105
	s_nop 0
	v_add_f32_e32 v105, 1.0, v105
	v_rcp_f32_e32 v108, v105
	v_mul_f32_e32 v105, 0xbfb8aa3b, v111
	v_exp_f32_e32 v105, v105
	s_nop 0
	v_add_f32_e32 v105, 1.0, v105
	v_rcp_f32_e32 v109, v105
	s_nop 0
	v_pk_mul_f32 v[108:109], v[110:111], v[108:109]
	s_nop 0
	v_pk_mul_f32 v[106:107], v[108:109], v[106:107]
; __device__ __forceinline__ unsigned cvtpk(float lo, float hi) { const f32x2 v = (f32x2){lo, hi}; const bf16v2 b = __builtin_convertvector(v, bf16v2); return __builtin_bit_cast(unsigned, b); }
; __device__ __forceinline__ float siluf_(float x) { return x * sigmoidf_(x); }
;     __device__ __forceinline__ void operator()(const f32x4 (&acc)[2][2][4][2], const pg8::Unit& u, int wr, int wc, int fr, int fq) const {
;         const int row0 = u.pm * 256 + wr * 64 + fr, col0 = u.pn * 128 + wc * 32 + 8 * fq;
; #pragma unroll
;         for (int ai = 0; ai < 2; ++ai)
; #pragma unroll
;             for (int m = 0; m < 4; ++m) { bf16_t* rowp = O + (size_t)(row0 + ai * 128 + m * 16) * ldc + col0;
;                 const f32x4 g0 = acc[ai][0][m][0], g1 = acc[ai][0][m][1], u0 = acc[ai][1][m][0], u1 = acc[ai][1][m][1];
;                 u32x4 w; w.x = cvtpk(siluf_(g0[0]) * u0[0], siluf_(g0[1]) * u0[1]); w.y = cvtpk(siluf_(g0[2]) * u0[2], siluf_(g0[3]) * u0[3]);
;                 w.z = cvtpk(siluf_(g1[0]) * u1[0], siluf_(g1[1]) * u1[1]); w.w = cvtpk(siluf_(g1[2]) * u1[2], siluf_(g1[3]) * u1[3]);
;                 *(u32x4*)rowp = w; }
	s_nop 0
	v_cvt_pk_bf16_f32 v105, v106, v107
	v_mul_f32_e32 v106, 0xbfb8aa3b, v100
	v_mul_f32_e32 v107, 0xbfb8aa3b, v101
	v_exp_f32_e32 v106, v106
	v_exp_f32_e32 v107, v107
	v_add_f32_e32 v106, 1.0, v106
	v_add_f32_e32 v107, 1.0, v107
	v_rcp_f32_e32 v106, v106
	v_rcp_f32_e32 v107, v107
	s_nop 0
	v_pk_mul_f32 v[100:101], v[100:101], v[106:107]
	s_nop 0
	v_pk_mul_f32 v[96:97], v[100:101], v[96:97]
	s_nop 0
	v_cvt_pk_bf16_f32 v106, v96, v97
	v_mul_f32_e32 v96, 0xbfb8aa3b, v102
	v_mul_f32_e32 v97, 0xbfb8aa3b, v103
	v_exp_f32_e32 v96, v96
	v_exp_f32_e32 v97, v97
	v_add_f32_e32 v96, 1.0, v96
	v_add_f32_e32 v97, 1.0, v97
	v_rcp_f32_e32 v96, v96
	v_rcp_f32_e32 v97, v97
	s_nop 0
	v_pk_mul_f32 v[96:97], v[102:103], v[96:97]
	s_nop 0
	v_pk_mul_f32 v[96:97], v[96:97], v[98:99]
	v_mul_f32_e32 v98, 0xbfb8aa3b, v92
	v_mul_f32_e32 v99, 0xbfb8aa3b, v93
	v_exp_f32_e32 v98, v98
	v_exp_f32_e32 v99, v99
	v_cvt_pk_bf16_f32 v107, v96, v97
	v_or_b32_e32 v96, 32, v146
	v_add_f32_e32 v98, 1.0, v98
	v_add_f32_e32 v99, 1.0, v99
	v_rcp_f32_e32 v98, v98
	v_rcp_f32_e32 v99, v99
	v_mad_i64_i32 v[96:97], s[12:13], v96, s81, v[138:139]
	v_lshl_add_u64 v[96:97], v[96:97], 0, v[140:141]
	v_pk_mul_f32 v[92:93], v[92:93], v[98:99]
	global_store_dwordx4 v[112:113], v[104:107], off
	v_pk_mul_f32 v[88:89], v[92:93], v[88:89]
	s_nop 0
	v_cvt_pk_bf16_f32 v88, v88, v89
	v_mul_f32_e32 v89, 0xbfb8aa3b, v94
	v_exp_f32_e32 v89, v89
	s_nop 0
	v_add_f32_e32 v89, 1.0, v89
	v_rcp_f32_e32 v92, v89
	v_mul_f32_e32 v89, 0xbfb8aa3b, v95
	v_exp_f32_e32 v89, v89
	s_nop 0
	v_add_f32_e32 v89, 1.0, v89
	v_rcp_f32_e32 v93, v89
	s_nop 0
	v_pk_mul_f32 v[92:93], v[94:95], v[92:93]
	s_nop 0
	v_pk_mul_f32 v[90:91], v[92:93], v[90:91]
	s_nop 0
	v_cvt_pk_bf16_f32 v89, v90, v91
	v_mul_f32_e32 v90, 0xbfb8aa3b, v84
	v_mul_f32_e32 v91, 0xbfb8aa3b, v85
	v_exp_f32_e32 v90, v90
	v_exp_f32_e32 v91, v91
	v_add_f32_e32 v90, 1.0, v90
	v_add_f32_e32 v91, 1.0, v91
	v_rcp_f32_e32 v90, v90
	v_rcp_f32_e32 v91, v91
	s_nop 0
	v_pk_mul_f32 v[84:85], v[84:85], v[90:91]
	s_nop 0
	v_pk_mul_f32 v[80:81], v[84:85], v[80:81]
	s_nop 0
	v_cvt_pk_bf16_f32 v90, v80, v81
	v_mul_f32_e32 v80, 0xbfb8aa3b, v86
	v_mul_f32_e32 v81, 0xbfb8aa3b, v87
	v_exp_f32_e32 v80, v80
	v_exp_f32_e32 v81, v81
	v_add_f32_e32 v80, 1.0, v80
	v_add_f32_e32 v81, 1.0, v81
	v_rcp_f32_e32 v80, v80
	v_rcp_f32_e32 v81, v81
	s_nop 0
	v_pk_mul_f32 v[80:81], v[86:87], v[80:81]
	s_nop 0
	v_pk_mul_f32 v[80:81], v[80:81], v[82:83]
	v_mul_f32_e32 v82, 0xbfb8aa3b, v76
	v_mul_f32_e32 v83, 0xbfb8aa3b, v77
	v_exp_f32_e32 v82, v82
	v_exp_f32_e32 v83, v83
	v_cvt_pk_bf16_f32 v91, v80, v81
	v_or_b32_e32 v80, 48, v146
	v_add_f32_e32 v82, 1.0, v82
	v_add_f32_e32 v83, 1.0, v83
	v_rcp_f32_e32 v82, v82
	v_rcp_f32_e32 v83, v83
	v_mad_i64_i32 v[80:81], s[12:13], v80, s81, v[138:139]
	v_lshl_add_u64 v[80:81], v[80:81], 0, v[140:141]
	v_pk_mul_f32 v[76:77], v[76:77], v[82:83]
	global_store_dwordx4 v[96:97], v[88:91], off
	v_pk_mul_f32 v[72:73], v[76:77], v[72:73]
	s_nop 0
	v_cvt_pk_bf16_f32 v72, v72, v73
	v_mul_f32_e32 v73, 0xbfb8aa3b, v78
	v_exp_f32_e32 v73, v73
	s_nop 0
	v_add_f32_e32 v73, 1.0, v73
	v_rcp_f32_e32 v76, v73
	v_mul_f32_e32 v73, 0xbfb8aa3b, v79
	v_exp_f32_e32 v73, v73
	s_nop 0
	v_add_f32_e32 v73, 1.0, v73
	v_rcp_f32_e32 v77, v73
	s_nop 0
	v_pk_mul_f32 v[76:77], v[78:79], v[76:77]
	s_nop 0
	v_pk_mul_f32 v[74:75], v[76:77], v[74:75]
	s_nop 0
	v_cvt_pk_bf16_f32 v73, v74, v75
	v_mul_f32_e32 v74, 0xbfb8aa3b, v68
	v_mul_f32_e32 v75, 0xbfb8aa3b, v69
	v_exp_f32_e32 v74, v74
	v_exp_f32_e32 v75, v75
	v_add_f32_e32 v74, 1.0, v74
	v_add_f32_e32 v75, 1.0, v75
	v_rcp_f32_e32 v74, v74
	v_rcp_f32_e32 v75, v75
	s_nop 0
	v_pk_mul_f32 v[68:69], v[68:69], v[74:75]
	s_nop 0
	v_pk_mul_f32 v[64:65], v[68:69], v[64:65]
	s_nop 0
	v_cvt_pk_bf16_f32 v74, v64, v65
	v_mul_f32_e32 v64, 0xbfb8aa3b, v70
	v_mul_f32_e32 v65, 0xbfb8aa3b, v71
	v_exp_f32_e32 v64, v64
	v_exp_f32_e32 v65, v65
	v_add_f32_e32 v64, 1.0, v64
	v_add_f32_e32 v65, 1.0, v65
	v_rcp_f32_e32 v64, v64
	v_rcp_f32_e32 v65, v65
	s_nop 0
	v_pk_mul_f32 v[64:65], v[70:71], v[64:65]
	s_nop 0
	v_pk_mul_f32 v[64:65], v[64:65], v[66:67]
	v_mul_f32_e32 v66, 0xbfb8aa3b, v60
	v_mul_f32_e32 v67, 0xbfb8aa3b, v61
	v_exp_f32_e32 v66, v66
	v_exp_f32_e32 v67, v67
	v_cvt_pk_bf16_f32 v75, v64, v65
	v_add_u32_e32 v64, 0x80, v146
	v_add_f32_e32 v66, 1.0, v66
	v_add_f32_e32 v67, 1.0, v67
	v_rcp_f32_e32 v66, v66
	v_rcp_f32_e32 v67, v67
	v_mad_i64_i32 v[64:65], s[12:13], v64, s81, v[138:139]
	v_lshl_add_u64 v[64:65], v[64:65], 0, v[140:141]
	v_pk_mul_f32 v[60:61], v[60:61], v[66:67]
	global_store_dwordx4 v[80:81], v[72:75], off
	v_pk_mul_f32 v[56:57], v[60:61], v[56:57]
	s_nop 0
	v_cvt_pk_bf16_f32 v56, v56, v57
	v_mul_f32_e32 v57, 0xbfb8aa3b, v62
	v_exp_f32_e32 v57, v57
	s_nop 0
	v_add_f32_e32 v57, 1.0, v57
	v_rcp_f32_e32 v60, v57
	v_mul_f32_e32 v57, 0xbfb8aa3b, v63
	v_exp_f32_e32 v57, v57
	s_nop 0
	v_add_f32_e32 v57, 1.0, v57
	v_rcp_f32_e32 v61, v57
	s_nop 0
	v_pk_mul_f32 v[60:61], v[62:63], v[60:61]
	s_nop 0
	v_pk_mul_f32 v[58:59], v[60:61], v[58:59]
	s_nop 0
	v_cvt_pk_bf16_f32 v57, v58, v59
	v_mul_f32_e32 v58, 0xbfb8aa3b, v52
	v_mul_f32_e32 v59, 0xbfb8aa3b, v53
	v_exp_f32_e32 v58, v58
	v_exp_f32_e32 v59, v59
	v_add_f32_e32 v58, 1.0, v58
	v_add_f32_e32 v59, 1.0, v59
	v_rcp_f32_e32 v58, v58
	v_rcp_f32_e32 v59, v59
	s_nop 0
	v_pk_mul_f32 v[52:53], v[52:53], v[58:59]
	s_nop 0
	v_pk_mul_f32 v[48:49], v[52:53], v[48:49]
	s_nop 0
	v_cvt_pk_bf16_f32 v58, v48, v49
	v_mul_f32_e32 v48, 0xbfb8aa3b, v54
	v_mul_f32_e32 v49, 0xbfb8aa3b, v55
; __device__ __forceinline__ unsigned cvtpk(float lo, float hi) { const f32x2 v = (f32x2){lo, hi}; const bf16v2 b = __builtin_convertvector(v, bf16v2); return __builtin_bit_cast(unsigned, b); }
; __device__ __forceinline__ float siluf_(float x) { return x * sigmoidf_(x); }
; #define PG8_WAIT_V(n) asm volatile("s_waitcnt vmcnt(" #n ")" ::: "memory")
; #define PG8_BAR __builtin_amdgcn_s_barrier()
; template <class Epi, class Sched>
; __device__ __forceinline__ void gemm_phase(PG8_LAS unsigned char* lds, const Gemm g, const Sched& S, const Epi& E) {
;     ...
;         if constexpr (!Epi::AFTER_DRAIN) { E(acc, cur, wr, wc, fr, fq); S.done(cur); }
;         if (!has_next) break;
; #pragma unroll
;         for (int a = 0; a < 2; ++a)
; #pragma unroll
;             for (int b = 0; b < 2; ++b)
; #pragma unroll
;                 for (int m = 0; m < 4; ++m)
; #pragma unroll
;                     for (int n = 0; n < 2; ++n) acc[a][b][m][n] = (f32x4){0.f, 0.f, 0.f, 0.f};
;         cur = nxt; cA = nA; cB = nB; ++ui;
;     }
;     PG8_WAIT_V(0);
;     if (wr == 0) PG8_BAR;
;     PG8_BAR;
;     __device__ __forceinline__ void operator()(const f32x4 (&acc)[2][2][4][2], const pg8::Unit& u, int wr, int wc, int fr, int fq) const {
;         const int row0 = u.pm * 256 + wr * 64 + fr, col0 = u.pn * 128 + wc * 32 + 8 * fq;
; #pragma unroll
;         for (int ai = 0; ai < 2; ++ai)
; #pragma unroll
;             for (int m = 0; m < 4; ++m) { bf16_t* rowp = O + (size_t)(row0 + ai * 128 + m * 16) * ldc + col0;
;                 const f32x4 g0 = acc[ai][0][m][0], g1 = acc[ai][0][m][1], u0 = acc[ai][1][m][0], u1 = acc[ai][1][m][1];
;                 u32x4 w; w.x = cvtpk(siluf_(g0[0]) * u0[0], siluf_(g0[1]) * u0[1]); w.y = cvtpk(siluf_(g0[2]) * u0[2], siluf_(g0[3]) * u0[3]);
;                 w.z = cvtpk(siluf_(g1[0]) * u1[0], siluf_(g1[1]) * u1[1]); w.w = cvtpk(siluf_(g1[2]) * u1[2], siluf_(g1[3]) * u1[3]);
;                 *(u32x4*)rowp = w; }
	v_exp_f32_e32 v48, v48
	v_exp_f32_e32 v49, v49
	v_add_f32_e32 v48, 1.0, v48
	v_add_f32_e32 v49, 1.0, v49
	v_rcp_f32_e32 v48, v48
	v_rcp_f32_e32 v49, v49
	s_nop 0
	v_pk_mul_f32 v[48:49], v[54:55], v[48:49]
	s_nop 0
	v_pk_mul_f32 v[48:49], v[48:49], v[50:51]
	v_mul_f32_e32 v50, 0xbfb8aa3b, v44
	v_mul_f32_e32 v51, 0xbfb8aa3b, v45
	v_exp_f32_e32 v50, v50
	v_exp_f32_e32 v51, v51
	v_cvt_pk_bf16_f32 v59, v48, v49
	v_add_u32_e32 v48, 0x90, v146
	v_add_f32_e32 v50, 1.0, v50
	v_add_f32_e32 v51, 1.0, v51
	v_rcp_f32_e32 v50, v50
	v_rcp_f32_e32 v51, v51
	v_mad_i64_i32 v[48:49], s[12:13], v48, s81, v[138:139]
	v_lshl_add_u64 v[48:49], v[48:49], 0, v[140:141]
	v_pk_mul_f32 v[44:45], v[44:45], v[50:51]
	global_store_dwordx4 v[64:65], v[56:59], off
	v_pk_mul_f32 v[40:41], v[44:45], v[40:41]
	s_nop 0
	v_cvt_pk_bf16_f32 v40, v40, v41
	v_mul_f32_e32 v41, 0xbfb8aa3b, v46
	v_exp_f32_e32 v41, v41
	s_nop 0
	v_add_f32_e32 v41, 1.0, v41
	v_rcp_f32_e32 v44, v41
	v_mul_f32_e32 v41, 0xbfb8aa3b, v47
	v_exp_f32_e32 v41, v41
	s_nop 0
	v_add_f32_e32 v41, 1.0, v41
	v_rcp_f32_e32 v45, v41
	s_nop 0
	v_pk_mul_f32 v[44:45], v[46:47], v[44:45]
	s_nop 0
	v_pk_mul_f32 v[42:43], v[44:45], v[42:43]
	s_nop 0
	v_cvt_pk_bf16_f32 v41, v42, v43
	v_mul_f32_e32 v42, 0xbfb8aa3b, v36
	v_mul_f32_e32 v43, 0xbfb8aa3b, v37
	v_exp_f32_e32 v42, v42
	v_exp_f32_e32 v43, v43
	v_add_f32_e32 v42, 1.0, v42
	v_add_f32_e32 v43, 1.0, v43
	v_rcp_f32_e32 v42, v42
	v_rcp_f32_e32 v43, v43
	s_nop 0
	v_pk_mul_f32 v[36:37], v[36:37], v[42:43]
	s_nop 0
	v_pk_mul_f32 v[32:33], v[36:37], v[32:33]
	s_nop 0
	v_cvt_pk_bf16_f32 v42, v32, v33
	v_mul_f32_e32 v32, 0xbfb8aa3b, v38
	v_mul_f32_e32 v33, 0xbfb8aa3b, v39
	v_exp_f32_e32 v32, v32
	v_exp_f32_e32 v33, v33
	v_add_f32_e32 v32, 1.0, v32
	v_add_f32_e32 v33, 1.0, v33
	v_rcp_f32_e32 v32, v32
	v_rcp_f32_e32 v33, v33
	s_nop 0
	v_pk_mul_f32 v[32:33], v[38:39], v[32:33]
	s_nop 0
	v_pk_mul_f32 v[32:33], v[32:33], v[34:35]
	v_mul_f32_e32 v34, 0xbfb8aa3b, v28
	v_mul_f32_e32 v35, 0xbfb8aa3b, v29
	v_exp_f32_e32 v34, v34
	v_exp_f32_e32 v35, v35
	v_cvt_pk_bf16_f32 v43, v32, v33
	v_add_u32_e32 v32, 0xa0, v146
	v_add_f32_e32 v34, 1.0, v34
	v_add_f32_e32 v35, 1.0, v35
	v_rcp_f32_e32 v34, v34
	v_rcp_f32_e32 v35, v35
	v_mad_i64_i32 v[32:33], s[12:13], v32, s81, v[138:139]
	v_lshl_add_u64 v[32:33], v[32:33], 0, v[140:141]
	v_pk_mul_f32 v[28:29], v[28:29], v[34:35]
	global_store_dwordx4 v[48:49], v[40:43], off
	v_pk_mul_f32 v[24:25], v[28:29], v[24:25]
	s_nop 0
	v_cvt_pk_bf16_f32 v24, v24, v25
	v_mul_f32_e32 v25, 0xbfb8aa3b, v30
	v_exp_f32_e32 v25, v25
	s_nop 0
	v_add_f32_e32 v25, 1.0, v25
	v_rcp_f32_e32 v28, v25
	v_mul_f32_e32 v25, 0xbfb8aa3b, v31
	v_exp_f32_e32 v25, v25
	s_nop 0
	v_add_f32_e32 v25, 1.0, v25
	v_rcp_f32_e32 v29, v25
	s_nop 0
	v_pk_mul_f32 v[28:29], v[30:31], v[28:29]
	s_nop 0
	v_pk_mul_f32 v[26:27], v[28:29], v[26:27]
	s_nop 0
	v_cvt_pk_bf16_f32 v25, v26, v27
	v_mul_f32_e32 v26, 0xbfb8aa3b, v20
	v_mul_f32_e32 v27, 0xbfb8aa3b, v21
	v_exp_f32_e32 v26, v26
	v_exp_f32_e32 v27, v27
	v_add_f32_e32 v26, 1.0, v26
	v_add_f32_e32 v27, 1.0, v27
	v_rcp_f32_e32 v26, v26
	v_rcp_f32_e32 v27, v27
	s_nop 0
	v_pk_mul_f32 v[20:21], v[20:21], v[26:27]
	s_nop 0
	v_pk_mul_f32 v[16:17], v[20:21], v[16:17]
	s_nop 0
	v_cvt_pk_bf16_f32 v26, v16, v17
	v_mul_f32_e32 v16, 0xbfb8aa3b, v22
	v_mul_f32_e32 v17, 0xbfb8aa3b, v23
	v_exp_f32_e32 v16, v16
	v_exp_f32_e32 v17, v17
	v_add_f32_e32 v16, 1.0, v16
	v_add_f32_e32 v17, 1.0, v17
	v_rcp_f32_e32 v16, v16
	v_rcp_f32_e32 v17, v17
	s_nop 0
	v_pk_mul_f32 v[16:17], v[22:23], v[16:17]
	s_nop 0
	v_pk_mul_f32 v[16:17], v[16:17], v[18:19]
	v_mul_f32_e32 v18, 0xbfb8aa3b, v12
	v_mul_f32_e32 v19, 0xbfb8aa3b, v13
	v_exp_f32_e32 v18, v18
	v_exp_f32_e32 v19, v19
	v_cvt_pk_bf16_f32 v27, v16, v17
	v_add_u32_e32 v16, 0xb0, v146
	v_add_f32_e32 v18, 1.0, v18
	v_add_f32_e32 v19, 1.0, v19
	v_rcp_f32_e32 v18, v18
	v_rcp_f32_e32 v19, v19
	v_mad_i64_i32 v[16:17], s[12:13], v16, s81, v[138:139]
	v_lshl_add_u64 v[16:17], v[16:17], 0, v[140:141]
	v_pk_mul_f32 v[12:13], v[12:13], v[18:19]
	s_mov_b64 s[12:13], s[6:7]
	v_pk_mul_f32 v[8:9], v[12:13], v[8:9]
	global_store_dwordx4 v[32:33], v[24:27], off
	v_cvt_pk_bf16_f32 v8, v8, v9
	v_mul_f32_e32 v9, 0xbfb8aa3b, v14
	v_exp_f32_e32 v9, v9
	s_nop 0
	v_add_f32_e32 v9, 1.0, v9
	v_rcp_f32_e32 v12, v9
	v_mul_f32_e32 v9, 0xbfb8aa3b, v15
	v_exp_f32_e32 v9, v9
	s_nop 0
	v_add_f32_e32 v9, 1.0, v9
	v_rcp_f32_e32 v13, v9
	s_nop 0
	v_pk_mul_f32 v[12:13], v[14:15], v[12:13]
	s_nop 0
	v_pk_mul_f32 v[10:11], v[12:13], v[10:11]
	s_nop 0
	v_cvt_pk_bf16_f32 v9, v10, v11
	v_mul_f32_e32 v10, 0xbfb8aa3b, v4
	v_mul_f32_e32 v11, 0xbfb8aa3b, v5
	v_exp_f32_e32 v10, v10
	v_exp_f32_e32 v11, v11
	v_add_f32_e32 v10, 1.0, v10
	v_add_f32_e32 v11, 1.0, v11
	v_rcp_f32_e32 v10, v10
	v_rcp_f32_e32 v11, v11
	s_nop 0
	v_pk_mul_f32 v[4:5], v[4:5], v[10:11]
	s_nop 0
	v_pk_mul_f32 v[0:1], v[4:5], v[0:1]
	s_nop 0
	v_cvt_pk_bf16_f32 v10, v0, v1
	v_mul_f32_e32 v0, 0xbfb8aa3b, v6
	v_mul_f32_e32 v1, 0xbfb8aa3b, v7
	v_exp_f32_e32 v0, v0
	v_exp_f32_e32 v1, v1
	v_add_f32_e32 v0, 1.0, v0
	v_add_f32_e32 v1, 1.0, v1
	v_rcp_f32_e32 v0, v0
	v_rcp_f32_e32 v1, v1
	s_nop 0
	v_pk_mul_f32 v[0:1], v[6:7], v[0:1]
	s_nop 0
	v_pk_mul_f32 v[0:1], v[0:1], v[2:3]
	s_nop 0
	v_cvt_pk_bf16_f32 v11, v0, v1
	global_store_dwordx4 v[16:17], v[8:11], off
	s_cbranch_vccz .LBB0_111
	s_waitcnt vmcnt(0)
	v_readlane_b32 s22, v255, 14
	s_cmpk_gt_u32 s19, 0xff
	v_readlane_b32 s23, v255, 15
	s_mov_b64 s[28:29], s[54:55]
	s_cbranch_scc1 .LBB0_118
	s_barrier

; #define PG8_STAGE(bufoff, gbase, voff) do { _Pragma("unroll") for (int _i = 0; _i < 2; ++_i) \
;         __builtin_amdgcn_global_load_lds((const unsigned*)((const char*)(gbase) + (voff)[_i]), (PG8_LAS unsigned*)(lds + (bufoff) + ldsw + _i * 8192), 16, 0, 0); } while (0)
; #define PG8_LDA(dst, b, h) do { _Pragma("unroll") for (int m = 0; m < 4; ++m) _Pragma("unroll") for (int k = 0; k < 2; ++k) dst[m][k] = *(const PG8_LAS bf16x8*)(lds + PG8_SA(b, h) + aoff + m * 2048 + k * 1024); } while (0)
; #define PG8_LDB(dst, b, h) do { _Pragma("unroll") for (int n = 0; n < 2; ++n) _Pragma("unroll") for (int k = 0; k < 2; ++k) dst[n][k] = *(const PG8_LAS bf16x8*)(lds + PG8_SB(b, h) + boff + n * 2048 + k * 1024); } while (0)
; #define PG8_WAIT_V(n) asm volatile("s_waitcnt vmcnt(" #n ")" ::: "memory")
; #define PG8_WAIT_L(n) asm volatile("s_waitcnt lgkmcnt(" #n ")" ::: "memory")
; #define PG8_BAR __builtin_amdgcn_s_barrier()
; #define PG8_SCHED __builtin_amdgcn_sched_barrier(0)
; template <class Epi, class Sched>
; __device__ __forceinline__ void gemm_phase(PG8_LAS unsigned char* lds, const Gemm g, const Sched& S, const Epi& E) {
;     ...
;         const bool has_next = S.next(ui + 1, nxt);
;         const char* nA = has_next ? (const char*)g.A + (size_t)nxt.pm * tstep : cA; const char* nB = has_next ? (const char*)g.Bt + (size_t)nxt.pn * tstep : cB;
;         for (int t = 0; t < nt; t += 2) {
;             const bool last = (t == nt - 2);
;             const char* a1 = cA + (size_t)(t + 1) * kstep;
;             const char* a2 = last ? nA : cA + (size_t)(t + 2) * kstep; const char* b2 = last ? nB : cB + (size_t)(t + 2) * kstep;
;             const char* a3 = a2 + kstep; const char* b3 = b2 + kstep;
;             if (last && has_next) S.a_ready(nxt);
;             PG8_LDB(B0, 0, 0); PG8_SCHED; PG8_LDA(At, 0, 0); PG8_STAGE(PG8_SA(1, 1), a1 + hstep, voffA);
;             PG8_WAIT_L(8); PG8_BAR; PG8_WAIT_L(0); PG8_MMA(0, 0, At, B0); PG8_BAR; PG8_SCHED;
;             PG8_LDB(B1, 0, 1); PG8_STAGE(PG8_SB(0, 0), b2, voffB);
;             PG8_BAR; PG8_WAIT_L(0); PG8_MMA(0, 1, At, B1); PG8_BAR;
;             PG8_LDA(At, 0, 1); PG8_STAGE(PG8_SA(0, 0), a2, voffA);
;             PG8_BAR; PG8_WAIT_L(0); PG8_MMA(1, 0, At, B0); PG8_BAR; PG8_SCHED;
;             PG8_STAGE(PG8_SB(0, 1), b2 + hstep, voffB);
;             PG8_WAIT_V(6); PG8_BAR; PG8_MMA(1, 1, At, B1); PG8_BAR;
.LBB0_137:
	s_add_u32 s14, s12, 0xfffc0080
	s_addc_u32 s15, s13, -1
	s_add_i32 s46, 0, 0x10000
	v_add_u32_e32 v154, s46, v139
	ds_read_b128 v[142:145], v154
	ds_read_b128 v[146:149], v154 offset:1024
	ds_read_b128 v[150:153], v154 offset:2048
	ds_read_b128 v[154:157], v154 offset:3072
	s_cmp_eq_u32 s45, 12
	s_cselect_b32 s17, s7, s15
	s_cselect_b32 s16, s40, s14
	s_cselect_b32 s15, s5, s44
	s_cselect_b32 s14, s41, s43
	s_add_i32 m0, s1, 0xc000
	ds_read_b128 v[158:161], v141
	ds_read_b128 v[162:165], v141 offset:1024
	ds_read_b128 v[166:169], v141 offset:2048
	ds_read_b128 v[170:173], v141 offset:3072
	ds_read_b128 v[178:181], v141 offset:4096
	ds_read_b128 v[182:185], v141 offset:5120
	ds_read_b128 v[186:189], v141 offset:6144
	ds_read_b128 v[190:193], v141 offset:7168
	global_load_lds_dwordx4 v134, s[12:13]
	s_add_i32 m0, s1, 0xe000
	s_nop 0
	global_load_lds_dwordx4 v136, s[12:13]
	s_waitcnt lgkmcnt(8)
	s_barrier
	s_waitcnt lgkmcnt(0)
	v_mfma_f32_16x16x32_bf16 v[124:127], v[142:145], v[158:161], v[124:127]
	v_mfma_f32_16x16x32_bf16 v[120:123], v[150:153], v[158:161], v[120:123]
	v_mfma_f32_16x16x32_bf16 v[116:119], v[142:145], v[166:169], v[116:119]
	v_mfma_f32_16x16x32_bf16 v[112:115], v[150:153], v[166:169], v[112:115]
	v_mfma_f32_16x16x32_bf16 v[100:103], v[142:145], v[178:181], v[100:103]
	v_mfma_f32_16x16x32_bf16 v[96:99], v[150:153], v[178:181], v[96:99]
	v_mfma_f32_16x16x32_bf16 v[84:87], v[142:145], v[186:189], v[84:87]
	v_mfma_f32_16x16x32_bf16 v[80:83], v[150:153], v[186:189], v[80:83]
	v_mfma_f32_16x16x32_bf16 v[124:127], v[146:149], v[162:165], v[124:127]
	v_mfma_f32_16x16x32_bf16 v[120:123], v[154:157], v[162:165], v[120:123]
	v_mfma_f32_16x16x32_bf16 v[116:119], v[146:149], v[170:173], v[116:119]
	v_mfma_f32_16x16x32_bf16 v[112:115], v[154:157], v[170:173], v[112:115]
	v_mfma_f32_16x16x32_bf16 v[100:103], v[146:149], v[182:185], v[100:103]
	v_mfma_f32_16x16x32_bf16 v[96:99], v[154:157], v[182:185], v[96:99]
	v_mfma_f32_16x16x32_bf16 v[84:87], v[146:149], v[190:193], v[84:87]
	v_mfma_f32_16x16x32_bf16 v[80:83], v[154:157], v[190:193], v[80:83]
	s_barrier
	s_add_i32 s48, 0, 0x14000
	v_add_u32_e32 v174, s48, v139
	s_add_i32 s46, s46, s20
	ds_read_b128 v[194:197], v174
	ds_read_b128 v[198:201], v174 offset:1024
	ds_read_b128 v[202:205], v174 offset:2048
	ds_read_b128 v[206:209], v174 offset:3072
	s_add_u32 s98, s14, 0x80
	s_addc_u32 s99, s15, 0
	s_mov_b32 m0, s46
	s_nop 0
	global_load_lds_dwordx4 v176, s[14:15]
	s_add_i32 m0, s46, 0x2000
	s_nop 0
	global_load_lds_dwordx4 v128, s[14:15]
	s_barrier
	s_waitcnt lgkmcnt(0)
	v_mfma_f32_16x16x32_bf16 v[108:111], v[194:197], v[158:161], v[108:111]
	v_mfma_f32_16x16x32_bf16 v[104:107], v[202:205], v[158:161], v[104:107]
	v_mfma_f32_16x16x32_bf16 v[92:95], v[194:197], v[166:169], v[92:95]
	v_mfma_f32_16x16x32_bf16 v[88:91], v[202:205], v[166:169], v[88:91]
	v_mfma_f32_16x16x32_bf16 v[76:79], v[194:197], v[178:181], v[76:79]
	v_mfma_f32_16x16x32_bf16 v[72:75], v[202:205], v[178:181], v[72:75]
	v_mfma_f32_16x16x32_bf16 v[68:71], v[194:197], v[186:189], v[68:71]
	v_mfma_f32_16x16x32_bf16 v[64:67], v[202:205], v[186:189], v[64:67]
	v_mfma_f32_16x16x32_bf16 v[108:111], v[198:201], v[162:165], v[108:111]
	v_mfma_f32_16x16x32_bf16 v[104:107], v[206:209], v[162:165], v[104:107]
	v_mfma_f32_16x16x32_bf16 v[92:95], v[198:201], v[170:173], v[92:95]
	v_mfma_f32_16x16x32_bf16 v[88:91], v[206:209], v[170:173], v[88:91]
	v_mfma_f32_16x16x32_bf16 v[76:79], v[198:201], v[182:185], v[76:79]
	v_mfma_f32_16x16x32_bf16 v[72:75], v[206:209], v[182:185], v[72:75]
	v_mfma_f32_16x16x32_bf16 v[68:71], v[198:201], v[190:193], v[68:71]
	v_mfma_f32_16x16x32_bf16 v[64:67], v[206:209], v[190:193], v[64:67]
	s_mov_b32 m0, s1
	s_add_u32 s100, s16, 0x80
	s_addc_u32 s101, s17, 0
	s_barrier
	ds_read_b128 v[158:161], v141 offset:16384
	ds_read_b128 v[162:165], v141 offset:17408
	ds_read_b128 v[166:169], v141 offset:18432
	ds_read_b128 v[170:173], v141 offset:19456
	ds_read_b128 v[178:181], v141 offset:20480
	ds_read_b128 v[182:185], v141 offset:21504
	ds_read_b128 v[186:189], v141 offset:22528
	ds_read_b128 v[190:193], v141 offset:23552
	global_load_lds_dwordx4 v132, s[16:17]
	s_mov_b32 m0, s22
	s_nop 0
	global_load_lds_dwordx4 v130, s[16:17]
	s_barrier
	s_waitcnt lgkmcnt(0)
	v_mfma_f32_16x16x32_bf16 v[60:63], v[142:145], v[158:161], v[60:63]
	v_mfma_f32_16x16x32_bf16 v[56:59], v[150:153], v[158:161], v[56:59]
	v_mfma_f32_16x16x32_bf16 v[52:55], v[142:145], v[166:169], v[52:55]
	v_mfma_f32_16x16x32_bf16 v[48:51], v[150:153], v[166:169], v[48:51]
	v_mfma_f32_16x16x32_bf16 v[36:39], v[142:145], v[178:181], v[36:39]
	v_mfma_f32_16x16x32_bf16 v[32:35], v[150:153], v[178:181], v[32:35]
	v_mfma_f32_16x16x32_bf16 v[20:23], v[142:145], v[186:189], v[20:23]
	v_mfma_f32_16x16x32_bf16 v[16:19], v[150:153], v[186:189], v[16:19]
	v_mfma_f32_16x16x32_bf16 v[60:63], v[146:149], v[162:165], v[60:63]
	v_mfma_f32_16x16x32_bf16 v[56:59], v[154:157], v[162:165], v[56:59]
	v_mfma_f32_16x16x32_bf16 v[52:55], v[146:149], v[170:173], v[52:55]
	v_mfma_f32_16x16x32_bf16 v[48:51], v[154:157], v[170:173], v[48:51]
	v_mfma_f32_16x16x32_bf16 v[36:39], v[146:149], v[182:185], v[36:39]
	v_mfma_f32_16x16x32_bf16 v[32:35], v[154:157], v[182:185], v[32:35]
	v_mfma_f32_16x16x32_bf16 v[20:23], v[146:149], v[190:193], v[20:23]
	v_mfma_f32_16x16x32_bf16 v[16:19], v[154:157], v[190:193], v[16:19]
	s_barrier
	s_add_u32 s46, s14, 0x40000
	s_addc_u32 s47, s15, 0
	s_add_i32 s48, s48, s20
	s_mov_b32 m0, s48
	s_nop 0
	global_load_lds_dwordx4 v176, s[46:47]
	s_add_i32 m0, s48, 0x2000
	s_nop 0
	global_load_lds_dwordx4 v128, s[46:47]
	s_waitcnt vmcnt(6)
	s_barrier
; #define PG8_STAGE(bufoff, gbase, voff) do { _Pragma("unroll") for (int _i = 0; _i < 2; ++_i) \
;         __builtin_amdgcn_global_load_lds((const unsigned*)((const char*)(gbase) + (voff)[_i]), (PG8_LAS unsigned*)(lds + (bufoff) + ldsw + _i * 8192), 16, 0, 0); } while (0)
; #define PG8_LDA(dst, b, h) do { _Pragma("unroll") for (int m = 0; m < 4; ++m) _Pragma("unroll") for (int k = 0; k < 2; ++k) dst[m][k] = *(const PG8_LAS bf16x8*)(lds + PG8_SA(b, h) + aoff + m * 2048 + k * 1024); } while (0)
; #define PG8_LDB(dst, b, h) do { _Pragma("unroll") for (int n = 0; n < 2; ++n) _Pragma("unroll") for (int k = 0; k < 2; ++k) dst[n][k] = *(const PG8_LAS bf16x8*)(lds + PG8_SB(b, h) + boff + n * 2048 + k * 1024); } while (0)
; #define PG8_MMA(ai, bj, At, Bt) do { __builtin_amdgcn_s_setprio(1); _Pragma("unroll") for (int m = 0; m < 4; ++m) _Pragma("unroll") for (int n = 0; n < 2; ++n) _Pragma("unroll") for (int k = 0; k < 2; ++k) \
;         acc[ai][bj][m][n] = __builtin_amdgcn_mfma_f32_16x16x32_bf16(Bt[n][k], At[m][k], acc[ai][bj][m][n], 0, 0, 0); __builtin_amdgcn_s_setprio(0); } while (0)
; #define PG8_WAIT_V(n) asm volatile("s_waitcnt vmcnt(" #n ")" ::: "memory")
; #define PG8_WAIT_L(n) asm volatile("s_waitcnt lgkmcnt(" #n ")" ::: "memory")
; #define PG8_BAR __builtin_amdgcn_s_barrier()
; #define PG8_SCHED __builtin_amdgcn_sched_barrier(0)
; template <class Epi, class Sched>
; __device__ __forceinline__ void gemm_phase(PG8_LAS unsigned char* lds, const Gemm g, const Sched& S, const Epi& E) {
;     ...
;             PG8_WAIT_V(6); PG8_BAR; PG8_MMA(1, 1, At, B1); PG8_BAR;
;             PG8_LDB(B0, 1, 0); PG8_SCHED; PG8_LDA(At, 1, 0); PG8_STAGE(PG8_SA(0, 1), a2 + hstep, voffA);
;             PG8_WAIT_L(8); PG8_BAR; PG8_WAIT_L(0); PG8_MMA(0, 0, At, B0); PG8_BAR; PG8_SCHED;
;             PG8_LDB(B1, 1, 1); PG8_STAGE(PG8_SB(1, 0), b3, voffB);
;             PG8_BAR; PG8_WAIT_L(0); PG8_MMA(0, 1, At, B1); PG8_BAR;
;             PG8_LDA(At, 1, 1); PG8_STAGE(PG8_SA(1, 0), a3, voffA);
	v_mfma_f32_16x16x32_bf16 v[44:47], v[194:197], v[158:161], v[44:47]
	v_mfma_f32_16x16x32_bf16 v[40:43], v[202:205], v[158:161], v[40:43]
	v_mfma_f32_16x16x32_bf16 v[28:31], v[194:197], v[166:169], v[28:31]
	v_mfma_f32_16x16x32_bf16 v[24:27], v[202:205], v[166:169], v[24:27]
	v_mfma_f32_16x16x32_bf16 v[12:15], v[194:197], v[178:181], v[12:15]
	v_mfma_f32_16x16x32_bf16 v[8:11], v[202:205], v[178:181], v[8:11]
	v_mfma_f32_16x16x32_bf16 v[4:7], v[194:197], v[186:189], v[4:7]
	v_mfma_f32_16x16x32_bf16 v[0:3], v[202:205], v[186:189], v[0:3]
	v_mfma_f32_16x16x32_bf16 v[44:47], v[198:201], v[162:165], v[44:47]
	v_mfma_f32_16x16x32_bf16 v[40:43], v[206:209], v[162:165], v[40:43]
	v_mfma_f32_16x16x32_bf16 v[28:31], v[198:201], v[170:173], v[28:31]
	v_mfma_f32_16x16x32_bf16 v[24:27], v[206:209], v[170:173], v[24:27]
	v_mfma_f32_16x16x32_bf16 v[12:15], v[198:201], v[182:185], v[12:15]
	v_mfma_f32_16x16x32_bf16 v[8:11], v[206:209], v[182:185], v[8:11]
	v_mfma_f32_16x16x32_bf16 v[4:7], v[198:201], v[190:193], v[4:7]
	v_mfma_f32_16x16x32_bf16 v[0:3], v[206:209], v[190:193], v[0:3]
	s_add_i32 s46, 0, 0x18000
	v_add_u32_e32 v154, s46, v139
	s_barrier
	ds_read_b128 v[142:145], v154
	ds_read_b128 v[146:149], v154 offset:1024
	ds_read_b128 v[150:153], v154 offset:2048
	ds_read_b128 v[154:157], v154 offset:3072
	s_add_u32 s16, s16, 0x40000
	s_addc_u32 s17, s17, 0
	s_mov_b32 m0, s23
	ds_read_b128 v[158:161], v141 offset:32768
	ds_read_b128 v[162:165], v141 offset:33792
	ds_read_b128 v[166:169], v141 offset:34816
	ds_read_b128 v[170:173], v141 offset:35840
	ds_read_b128 v[178:181], v141 offset:36864
	ds_read_b128 v[182:185], v141 offset:37888
	ds_read_b128 v[186:189], v141 offset:38912
	ds_read_b128 v[190:193], v141 offset:39936
	global_load_lds_dwordx4 v132, s[16:17]
	s_mov_b32 m0, s26
	s_nop 0
	global_load_lds_dwordx4 v130, s[16:17]
	s_waitcnt lgkmcnt(8)
	s_barrier
	s_waitcnt lgkmcnt(0)
	v_mfma_f32_16x16x32_bf16 v[124:127], v[142:145], v[158:161], v[124:127]
	v_mfma_f32_16x16x32_bf16 v[120:123], v[150:153], v[158:161], v[120:123]
	v_mfma_f32_16x16x32_bf16 v[116:119], v[142:145], v[166:169], v[116:119]
	v_mfma_f32_16x16x32_bf16 v[112:115], v[150:153], v[166:169], v[112:115]
	v_mfma_f32_16x16x32_bf16 v[100:103], v[142:145], v[178:181], v[100:103]
	v_mfma_f32_16x16x32_bf16 v[96:99], v[150:153], v[178:181], v[96:99]
	v_mfma_f32_16x16x32_bf16 v[84:87], v[142:145], v[186:189], v[84:87]
	v_mfma_f32_16x16x32_bf16 v[80:83], v[150:153], v[186:189], v[80:83]
	v_mfma_f32_16x16x32_bf16 v[124:127], v[146:149], v[162:165], v[124:127]
	v_mfma_f32_16x16x32_bf16 v[120:123], v[154:157], v[162:165], v[120:123]
	v_mfma_f32_16x16x32_bf16 v[116:119], v[146:149], v[170:173], v[116:119]
	v_mfma_f32_16x16x32_bf16 v[112:115], v[154:157], v[170:173], v[112:115]
	v_mfma_f32_16x16x32_bf16 v[100:103], v[146:149], v[182:185], v[100:103]
	v_mfma_f32_16x16x32_bf16 v[96:99], v[154:157], v[182:185], v[96:99]
	v_mfma_f32_16x16x32_bf16 v[84:87], v[146:149], v[190:193], v[84:87]
	v_mfma_f32_16x16x32_bf16 v[80:83], v[154:157], v[190:193], v[80:83]
	s_barrier
	s_add_i32 s16, 0, 0x1c000
	s_add_i32 s17, s46, s20
	v_add_u32_e32 v206, s16, v139
	s_mov_b32 m0, s17
	ds_read_b128 v[194:197], v206
	ds_read_b128 v[198:201], v206 offset:1024
	ds_read_b128 v[202:205], v206 offset:2048
	ds_read_b128 v[206:209], v206 offset:3072
	global_load_lds_dwordx4 v176, s[98:99]
	s_add_i32 m0, s17, 0x2000
	s_nop 0
	global_load_lds_dwordx4 v128, s[98:99]
	s_barrier
	s_waitcnt lgkmcnt(0)
	v_mfma_f32_16x16x32_bf16 v[108:111], v[194:197], v[158:161], v[108:111]
	v_mfma_f32_16x16x32_bf16 v[104:107], v[202:205], v[158:161], v[104:107]
	v_mfma_f32_16x16x32_bf16 v[92:95], v[194:197], v[166:169], v[92:95]
	v_mfma_f32_16x16x32_bf16 v[88:91], v[202:205], v[166:169], v[88:91]
	v_mfma_f32_16x16x32_bf16 v[76:79], v[194:197], v[178:181], v[76:79]
	v_mfma_f32_16x16x32_bf16 v[72:75], v[202:205], v[178:181], v[72:75]
	v_mfma_f32_16x16x32_bf16 v[68:71], v[194:197], v[186:189], v[68:71]
	v_mfma_f32_16x16x32_bf16 v[64:67], v[202:205], v[186:189], v[64:67]
	v_mfma_f32_16x16x32_bf16 v[108:111], v[198:201], v[162:165], v[108:111]
	v_mfma_f32_16x16x32_bf16 v[104:107], v[206:209], v[162:165], v[104:107]
	v_mfma_f32_16x16x32_bf16 v[92:95], v[198:201], v[170:173], v[92:95]
	v_mfma_f32_16x16x32_bf16 v[88:91], v[206:209], v[170:173], v[88:91]
	v_mfma_f32_16x16x32_bf16 v[76:79], v[198:201], v[182:185], v[76:79]
	v_mfma_f32_16x16x32_bf16 v[72:75], v[206:209], v[182:185], v[72:75]
	v_mfma_f32_16x16x32_bf16 v[68:71], v[198:201], v[190:193], v[68:71]
	v_mfma_f32_16x16x32_bf16 v[64:67], v[206:209], v[190:193], v[64:67]
	s_mov_b32 m0, s28
	s_barrier
	ds_read_b128 v[158:161], v141 offset:49152
	ds_read_b128 v[162:165], v141 offset:50176
	ds_read_b128 v[166:169], v141 offset:51200
	ds_read_b128 v[170:173], v141 offset:52224
	ds_read_b128 v[178:181], v141 offset:53248
	ds_read_b128 v[182:185], v141 offset:54272
	ds_read_b128 v[186:189], v141 offset:55296
	ds_read_b128 v[190:193], v141 offset:56320
	global_load_lds_dwordx4 v132, s[100:101]
	s_mov_b32 m0, s29
	s_nop 0
	global_load_lds_dwordx4 v130, s[100:101]
	s_barrier
; #define PG8_STAGE(bufoff, gbase, voff) do { _Pragma("unroll") for (int _i = 0; _i < 2; ++_i) \
;         __builtin_amdgcn_global_load_lds((const unsigned*)((const char*)(gbase) + (voff)[_i]), (PG8_LAS unsigned*)(lds + (bufoff) + ldsw + _i * 8192), 16, 0, 0); } while (0)
; #define PG8_LDA(dst, b, h) do { _Pragma("unroll") for (int m = 0; m < 4; ++m) _Pragma("unroll") for (int k = 0; k < 2; ++k) dst[m][k] = *(const PG8_LAS bf16x8*)(lds + PG8_SA(b, h) + aoff + m * 2048 + k * 1024); } while (0)
; #define PG8_MMA(ai, bj, At, Bt) do { __builtin_amdgcn_s_setprio(1); _Pragma("unroll") for (int m = 0; m < 4; ++m) _Pragma("unroll") for (int n = 0; n < 2; ++n) _Pragma("unroll") for (int k = 0; k < 2; ++k) \
;         acc[ai][bj][m][n] = __builtin_amdgcn_mfma_f32_16x16x32_bf16(Bt[n][k], At[m][k], acc[ai][bj][m][n], 0, 0, 0); __builtin_amdgcn_s_setprio(0); } while (0)
; #define PG8_WAIT_V(n) asm volatile("s_waitcnt vmcnt(" #n ")" ::: "memory")
; #define PG8_WAIT_L(n) asm volatile("s_waitcnt lgkmcnt(" #n ")" ::: "memory")
; #define PG8_BAR __builtin_amdgcn_s_barrier()
; #define PG8_SCHED __builtin_amdgcn_sched_barrier(0)
; template <class Epi, class Sched>
; __device__ __forceinline__ void gemm_phase(PG8_LAS unsigned char* lds, const Gemm g, const Sched& S, const Epi& E) {
;     ...
;             PG8_LDA(At, 1, 1); PG8_STAGE(PG8_SA(1, 0), a3, voffA);
;             PG8_BAR; PG8_WAIT_L(0); PG8_MMA(1, 0, At, B0); PG8_BAR; PG8_SCHED;
;             PG8_STAGE(PG8_SB(1, 1), b3 + hstep, voffB);
;             PG8_WAIT_V(6); PG8_BAR; PG8_MMA(1, 1, At, B1); PG8_BAR;
;         }
	s_waitcnt lgkmcnt(0)
	v_mfma_f32_16x16x32_bf16 v[60:63], v[142:145], v[158:161], v[60:63]
	v_mfma_f32_16x16x32_bf16 v[56:59], v[150:153], v[158:161], v[56:59]
	v_mfma_f32_16x16x32_bf16 v[52:55], v[142:145], v[166:169], v[52:55]
	v_mfma_f32_16x16x32_bf16 v[48:51], v[150:153], v[166:169], v[48:51]
	v_mfma_f32_16x16x32_bf16 v[36:39], v[142:145], v[178:181], v[36:39]
	v_mfma_f32_16x16x32_bf16 v[32:35], v[150:153], v[178:181], v[32:35]
	v_mfma_f32_16x16x32_bf16 v[20:23], v[142:145], v[186:189], v[20:23]
	v_mfma_f32_16x16x32_bf16 v[16:19], v[150:153], v[186:189], v[16:19]
	v_mfma_f32_16x16x32_bf16 v[60:63], v[146:149], v[162:165], v[60:63]
	v_mfma_f32_16x16x32_bf16 v[56:59], v[154:157], v[162:165], v[56:59]
	v_mfma_f32_16x16x32_bf16 v[52:55], v[146:149], v[170:173], v[52:55]
	v_mfma_f32_16x16x32_bf16 v[48:51], v[154:157], v[170:173], v[48:51]
	v_mfma_f32_16x16x32_bf16 v[36:39], v[146:149], v[182:185], v[36:39]
	v_mfma_f32_16x16x32_bf16 v[32:35], v[154:157], v[182:185], v[32:35]
	v_mfma_f32_16x16x32_bf16 v[20:23], v[146:149], v[190:193], v[20:23]
	v_mfma_f32_16x16x32_bf16 v[16:19], v[154:157], v[190:193], v[16:19]
	s_barrier
	s_add_u32 s14, s14, 0x40080
	s_addc_u32 s15, s15, 0
	s_add_i32 s16, s16, s20
	s_mov_b32 m0, s16
	s_nop 0
	global_load_lds_dwordx4 v176, s[14:15]
	s_add_i32 m0, s16, 0x2000
	s_nop 0
	global_load_lds_dwordx4 v128, s[14:15]
	s_waitcnt vmcnt(6)
	s_barrier
	v_mfma_f32_16x16x32_bf16 v[44:47], v[194:197], v[158:161], v[44:47]
	v_mfma_f32_16x16x32_bf16 v[40:43], v[202:205], v[158:161], v[40:43]
	v_mfma_f32_16x16x32_bf16 v[28:31], v[194:197], v[166:169], v[28:31]
	v_mfma_f32_16x16x32_bf16 v[24:27], v[202:205], v[166:169], v[24:27]
	v_mfma_f32_16x16x32_bf16 v[12:15], v[194:197], v[178:181], v[12:15]
	v_mfma_f32_16x16x32_bf16 v[8:11], v[202:205], v[178:181], v[8:11]
	v_mfma_f32_16x16x32_bf16 v[4:7], v[194:197], v[186:189], v[4:7]
	v_mfma_f32_16x16x32_bf16 v[0:3], v[202:205], v[186:189], v[0:3]
	v_mfma_f32_16x16x32_bf16 v[44:47], v[198:201], v[162:165], v[44:47]
	v_mfma_f32_16x16x32_bf16 v[40:43], v[206:209], v[162:165], v[40:43]
	v_mfma_f32_16x16x32_bf16 v[28:31], v[198:201], v[170:173], v[28:31]
	v_mfma_f32_16x16x32_bf16 v[24:27], v[206:209], v[170:173], v[24:27]
	v_mfma_f32_16x16x32_bf16 v[12:15], v[198:201], v[182:185], v[12:15]
	v_mfma_f32_16x16x32_bf16 v[8:11], v[206:209], v[182:185], v[8:11]
	v_mfma_f32_16x16x32_bf16 v[4:7], v[198:201], v[190:193], v[4:7]
	v_mfma_f32_16x16x32_bf16 v[0:3], v[206:209], v[190:193], v[0:3]
	s_add_i32 s45, s45, 2
	s_add_u32 s12, s12, 0x100
	s_addc_u32 s13, s13, 0
	s_add_u32 s43, s43, 0x100
	s_addc_u32 s44, s44, 0
	s_cmp_gt_u32 s45, 13
	s_barrier
	s_cbranch_scc0 .LBB0_137
; __device__ __forceinline__ unsigned cvtpk(float lo, float hi) { const f32x2 v = (f32x2){lo, hi}; const bf16v2 b = __builtin_convertvector(v, bf16v2); return __builtin_bit_cast(unsigned, b); }
; #define PG8_WAIT_V(n) asm volatile("s_waitcnt vmcnt(" #n ")" ::: "memory")
; #define PG8_BAR __builtin_amdgcn_s_barrier()
; template <class Epi, class Sched>
; __device__ __forceinline__ void gemm_phase(PG8_LAS unsigned char* lds, const Gemm g, const Sched& S, const Epi& E) {
;     ...
;         if constexpr (!Epi::AFTER_DRAIN) { E(acc, cur, wr, wc, fr, fq); S.done(cur); }
;         if (!has_next) break;
; #pragma unroll
;         for (int a = 0; a < 2; ++a)
; #pragma unroll
;             for (int b = 0; b < 2; ++b)
; #pragma unroll
;                 for (int m = 0; m < 4; ++m)
; #pragma unroll
;                     for (int n = 0; n < 2; ++n) acc[a][b][m][n] = (f32x4){0.f, 0.f, 0.f, 0.f};
;         cur = nxt; cA = nA; cB = nB; ++ui;
;     }
;     PG8_WAIT_V(0);
;     if (wr == 0) PG8_BAR;
;     PG8_BAR;
;     __device__ __forceinline__ void operator()(const f32x4 (&acc)[2][2][4][2], const pg8::Unit& u, int wr, int wc, int fr, int fq) const {
;         const int row0 = u.pm * 256 + wr * 64 + fr, col0 = u.pn * 256 + wc * 32 + 8 * fq;
; #pragma unroll
;         for (int ai = 0; ai < 2; ++ai)
; #pragma unroll
;             for (int m = 0; m < 4; ++m) { bf16_t* rowp = O + (size_t)(row0 + ai * 128 + m * 16) * ldc + col0;
; #pragma unroll
;                 for (int bj = 0; bj < 2; ++bj) { const f32x4 v0 = acc[ai][bj][m][0], v1 = acc[ai][bj][m][1];
;                     u32x4 w; w.x = cvtpk(v0[0], v0[1]); w.y = cvtpk(v0[2], v0[3]); w.z = cvtpk(v1[0], v1[1]); w.w = cvtpk(v1[2], v1[3]);
;                     *(u32x4*)(rowp + bj * 128) = w; } }
	v_lshl_add_u32 v142, s0, 8, v138
	v_lshl_or_b32 v144, s34, 8, v140
	v_ashrrev_i32_e32 v143, 31, v142
	v_readlane_b32 s12, v253, 18
	v_ashrrev_i32_e32 v145, 31, v144
	v_lshlrev_b64 v[146:147], 11, v[142:143]
	v_readlane_b32 s13, v253, 19
	v_cvt_pk_bf16_f32 v108, v108, v109
	v_cvt_pk_bf16_f32 v109, v110, v111
	v_cvt_pk_bf16_f32 v110, v104, v105
	v_or_b32_e32 v104, 16, v142
	v_cvt_pk_bf16_f32 v92, v92, v93
	v_cvt_pk_bf16_f32 v93, v94, v95
	v_cvt_pk_bf16_f32 v94, v88, v89
	v_or_b32_e32 v88, 32, v142
	v_cvt_pk_bf16_f32 v76, v76, v77
	v_cvt_pk_bf16_f32 v77, v78, v79
	v_cvt_pk_bf16_f32 v78, v72, v73
	v_or_b32_e32 v72, 48, v142
	v_lshl_add_u64 v[146:147], s[12:13], 0, v[146:147]
	v_lshlrev_b64 v[144:145], 1, v[144:145]
	v_ashrrev_i32_e32 v105, 31, v104
	v_ashrrev_i32_e32 v89, 31, v88
	v_ashrrev_i32_e32 v73, 31, v72
	v_lshl_add_u64 v[146:147], v[146:147], 0, v[144:145]
	v_lshlrev_b64 v[104:105], 11, v[104:105]
	v_lshlrev_b64 v[88:89], 11, v[88:89]
	v_lshlrev_b64 v[72:73], 11, v[72:73]
	v_lshl_add_u64 v[104:105], s[12:13], 0, v[104:105]
	v_lshl_add_u64 v[88:89], s[12:13], 0, v[88:89]
	v_lshl_add_u64 v[72:73], s[12:13], 0, v[72:73]
	s_mov_b64 s[12:13], 0x40000
	v_cvt_pk_bf16_f32 v60, v60, v61
	v_cvt_pk_bf16_f32 v61, v62, v63
	v_cvt_pk_bf16_f32 v62, v56, v57
	v_add_co_u32_e32 v56, vcc, s2, v146
	v_cvt_pk_bf16_f32 v68, v68, v69
	v_cvt_pk_bf16_f32 v69, v70, v71
	v_cvt_pk_bf16_f32 v70, v64, v65
	v_lshl_add_u64 v[64:65], v[146:147], 0, s[12:13]
	v_addc_co_u32_e32 v57, vcc, 0, v147, vcc
	v_cvt_pk_bf16_f32 v44, v44, v45
	v_cvt_pk_bf16_f32 v45, v46, v47
	v_cvt_pk_bf16_f32 v46, v40, v41
	v_cvt_pk_bf16_f32 v47, v42, v43
	s_mov_b32 s0, 0x48000
	global_store_dwordx4 v[64:65], v[44:47], off offset:256
	s_mov_b64 s[12:13], 0x48000
	v_cvt_pk_bf16_f32 v28, v28, v29
	v_add_co_u32_e32 v46, vcc, s0, v146
	v_lshl_add_u64 v[44:45], v[146:147], 0, s[12:13]
	s_nop 0
	v_addc_co_u32_e32 v47, vcc, 0, v147, vcc
	v_cvt_pk_bf16_f32 v29, v30, v31
	v_cvt_pk_bf16_f32 v30, v24, v25
	v_cvt_pk_bf16_f32 v31, v26, v27
	s_mov_b32 s0, 0x50000
	global_store_dwordx4 v[44:45], v[28:31], off offset:256
	s_mov_b64 s[12:13], 0x50000
	v_cvt_pk_bf16_f32 v111, v106, v107
	v_add_co_u32_e32 v30, vcc, s0, v146
	v_lshl_add_u64 v[28:29], v[146:147], 0, s[12:13]
	s_nop 0
	v_addc_co_u32_e32 v31, vcc, 0, v147, vcc
	v_cvt_pk_bf16_f32 v12, v12, v13
	v_cvt_pk_bf16_f32 v13, v14, v15
	v_cvt_pk_bf16_f32 v14, v8, v9
	v_cvt_pk_bf16_f32 v15, v10, v11
	s_mov_b32 s0, 0x58000
	global_store_dwordx4 v[146:147], v[108:111], off offset:256
	v_cvt_pk_bf16_f32 v95, v90, v91
	global_store_dwordx4 v[28:29], v[12:15], off offset:256
	v_lshl_add_u64 v[108:109], v[104:105], 0, v[144:145]
	global_store_dwordx4 v[108:109], v[92:95], off offset:256
	v_add_co_u32_e32 v14, vcc, s0, v146
	s_nop 0
	v_lshl_add_u64 v[92:93], v[88:89], 0, v[144:145]
	v_cvt_pk_bf16_f32 v79, v74, v75
	s_mov_b64 s[12:13], 0x58000
	v_addc_co_u32_e32 v15, vcc, 0, v147, vcc
	v_cvt_pk_bf16_f32 v124, v124, v125
	v_cvt_pk_bf16_f32 v125, v126, v127
	v_cvt_pk_bf16_f32 v126, v120, v121
	v_cvt_pk_bf16_f32 v127, v122, v123
	v_cvt_pk_bf16_f32 v104, v116, v117
	v_cvt_pk_bf16_f32 v105, v118, v119
	v_cvt_pk_bf16_f32 v106, v112, v113
	v_cvt_pk_bf16_f32 v107, v114, v115
	v_cvt_pk_bf16_f32 v88, v100, v101
	v_cvt_pk_bf16_f32 v89, v102, v103
	v_cvt_pk_bf16_f32 v90, v96, v97
	v_cvt_pk_bf16_f32 v91, v98, v99
	global_store_dwordx4 v[92:93], v[76:79], off offset:256
	v_cvt_pk_bf16_f32 v74, v80, v81
	v_cvt_pk_bf16_f32 v75, v82, v83
	v_lshl_add_u64 v[76:77], v[72:73], 0, v[144:145]
	v_cvt_pk_bf16_f32 v72, v84, v85
	v_cvt_pk_bf16_f32 v73, v86, v87
	v_cvt_pk_bf16_f32 v71, v66, v67
	v_cvt_pk_bf16_f32 v63, v58, v59
	v_cvt_pk_bf16_f32 v40, v52, v53
	v_cvt_pk_bf16_f32 v41, v54, v55
	v_cvt_pk_bf16_f32 v42, v48, v49
	v_cvt_pk_bf16_f32 v43, v50, v51
	v_cvt_pk_bf16_f32 v24, v36, v37
	v_cvt_pk_bf16_f32 v25, v38, v39
	v_cvt_pk_bf16_f32 v26, v32, v33
	v_cvt_pk_bf16_f32 v27, v34, v35
	v_lshl_add_u64 v[12:13], v[146:147], 0, s[12:13]
	v_cvt_pk_bf16_f32 v8, v20, v21
	v_cvt_pk_bf16_f32 v9, v22, v23
	v_cvt_pk_bf16_f32 v10, v16, v17
	v_cvt_pk_bf16_f32 v11, v18, v19
	v_cvt_pk_bf16_f32 v4, v4, v5
	v_cvt_pk_bf16_f32 v5, v6, v7
	v_cvt_pk_bf16_f32 v6, v0, v1
	v_cvt_pk_bf16_f32 v7, v2, v3
	s_and_b64 vcc, exec, s[38:39]
	s_mov_b32 s34, s4
	s_mov_b32 s0, s6
	s_mov_b64 s[14:15], s[10:11]
	s_mov_b64 s[12:13], s[8:9]
	global_store_dwordx4 v[146:147], v[124:127], off
	global_store_dwordx4 v[108:109], v[104:107], off
	global_store_dwordx4 v[92:93], v[88:91], off
	global_store_dwordx4 v[76:77], v[72:75], off
	global_store_dwordx4 v[76:77], v[68:71], off offset:256
	global_store_dwordx4 v[56:57], v[60:63], off
	global_store_dwordx4 v[46:47], v[40:43], off
	global_store_dwordx4 v[30:31], v[24:27], off
	global_store_dwordx4 v[14:15], v[8:11], off
	global_store_dwordx4 v[12:13], v[4:7], off offset:256
	s_cbranch_vccz .LBB0_134
	s_waitcnt vmcnt(0)
	v_readlane_b32 s22, v255, 14
	s_cmpk_gt_u32 s19, 0xff
	v_readlane_b32 s23, v255, 15
	s_mov_b64 s[28:29], s[54:55]
	s_cbranch_scc1 .LBB0_141
	s_barrier

; #define PG8_STAGE(bufoff, gbase, voff) do { _Pragma("unroll") for (int _i = 0; _i < 2; ++_i) \
;         __builtin_amdgcn_global_load_lds((const unsigned*)((const char*)(gbase) + (voff)[_i]), (PG8_LAS unsigned*)(lds + (bufoff) + ldsw + _i * 8192), 16, 0, 0); } while (0)
; #define PG8_LDA(dst, b, h) do { _Pragma("unroll") for (int m = 0; m < 4; ++m) _Pragma("unroll") for (int k = 0; k < 2; ++k) dst[m][k] = *(const PG8_LAS bf16x8*)(lds + PG8_SA(b, h) + aoff + m * 2048 + k * 1024); } while (0)
; #define PG8_LDB(dst, b, h) do { _Pragma("unroll") for (int n = 0; n < 2; ++n) _Pragma("unroll") for (int k = 0; k < 2; ++k) dst[n][k] = *(const PG8_LAS bf16x8*)(lds + PG8_SB(b, h) + boff + n * 2048 + k * 1024); } while (0)
; #define PG8_WAIT_V(n) asm volatile("s_waitcnt vmcnt(" #n ")" ::: "memory")
; #define PG8_WAIT_L(n) asm volatile("s_waitcnt lgkmcnt(" #n ")" ::: "memory")
; #define PG8_BAR __builtin_amdgcn_s_barrier()
; #define PG8_SCHED __builtin_amdgcn_sched_barrier(0)
; template <class Epi, class Sched>
; __device__ __forceinline__ void gemm_phase(PG8_LAS unsigned char* lds, const Gemm g, const Sched& S, const Epi& E) {
;     ...
;         const bool has_next = S.next(ui + 1, nxt);
;         const char* nA = has_next ? (const char*)g.A + (size_t)nxt.pm * tstep : cA; const char* nB = has_next ? (const char*)g.Bt + (size_t)nxt.pn * tstep : cB;
;         for (int t = 0; t < nt; t += 2) {
;             const bool last = (t == nt - 2);
;             const char* a1 = cA + (size_t)(t + 1) * kstep;
;             const char* a2 = last ? nA : cA + (size_t)(t + 2) * kstep; const char* b2 = last ? nB : cB + (size_t)(t + 2) * kstep;
;             const char* a3 = a2 + kstep; const char* b3 = b2 + kstep;
;             if (last && has_next) S.a_ready(nxt);
;             PG8_LDB(B0, 0, 0); PG8_SCHED; PG8_LDA(At, 0, 0); PG8_STAGE(PG8_SA(1, 1), a1 + hstep, voffA);
;             PG8_WAIT_L(8); PG8_BAR; PG8_WAIT_L(0); PG8_MMA(0, 0, At, B0); PG8_BAR; PG8_SCHED;
;             PG8_LDB(B1, 0, 1); PG8_STAGE(PG8_SB(0, 0), b2, voffB);
;             PG8_BAR; PG8_WAIT_L(0); PG8_MMA(0, 1, At, B1); PG8_BAR;
;             PG8_LDA(At, 0, 1); PG8_STAGE(PG8_SA(0, 0), a2, voffA);
;             PG8_BAR; PG8_WAIT_L(0); PG8_MMA(1, 0, At, B0); PG8_BAR; PG8_SCHED;
;             PG8_STAGE(PG8_SB(0, 1), b2 + hstep, voffB);
;             PG8_WAIT_V(6); PG8_BAR; PG8_MMA(1, 1, At, B1); PG8_BAR;
.LBB0_358:
	s_add_u32 s14, s12, 0xfffc0080
	s_addc_u32 s15, s13, -1
	s_add_i32 s46, 0, 0x10000
	v_add_u32_e32 v154, s46, v139
	ds_read_b128 v[142:145], v154
	ds_read_b128 v[146:149], v154 offset:1024
	ds_read_b128 v[150:153], v154 offset:2048
	ds_read_b128 v[154:157], v154 offset:3072
	s_cmp_eq_u32 s45, 12
	s_cselect_b32 s17, s7, s15
	s_cselect_b32 s16, s40, s14
	s_cselect_b32 s15, s5, s44
	s_cselect_b32 s14, s41, s43
	s_add_i32 m0, s1, 0xc000
	ds_read_b128 v[158:161], v141
	ds_read_b128 v[162:165], v141 offset:1024
	ds_read_b128 v[166:169], v141 offset:2048
	ds_read_b128 v[170:173], v141 offset:3072
	ds_read_b128 v[182:185], v141 offset:4096
	ds_read_b128 v[190:193], v141 offset:5120
	ds_read_b128 v[194:197], v141 offset:6144
	ds_read_b128 v[198:201], v141 offset:7168
	global_load_lds_dwordx4 v134, s[12:13]
	s_add_i32 m0, s1, 0xe000
	s_nop 0
	global_load_lds_dwordx4 v136, s[12:13]
	s_waitcnt lgkmcnt(8)
	s_barrier
	s_waitcnt lgkmcnt(0)
	v_mfma_f32_16x16x32_bf16 v[124:127], v[142:145], v[158:161], v[124:127]
	v_mfma_f32_16x16x32_bf16 v[120:123], v[150:153], v[158:161], v[120:123]
	v_mfma_f32_16x16x32_bf16 v[116:119], v[142:145], v[166:169], v[116:119]
	v_mfma_f32_16x16x32_bf16 v[112:115], v[150:153], v[166:169], v[112:115]
	v_mfma_f32_16x16x32_bf16 v[100:103], v[142:145], v[182:185], v[100:103]
	v_mfma_f32_16x16x32_bf16 v[96:99], v[150:153], v[182:185], v[96:99]
	v_mfma_f32_16x16x32_bf16 v[84:87], v[142:145], v[194:197], v[84:87]
	v_mfma_f32_16x16x32_bf16 v[80:83], v[150:153], v[194:197], v[80:83]
	v_mfma_f32_16x16x32_bf16 v[124:127], v[146:149], v[162:165], v[124:127]
	v_mfma_f32_16x16x32_bf16 v[120:123], v[154:157], v[162:165], v[120:123]
	v_mfma_f32_16x16x32_bf16 v[116:119], v[146:149], v[170:173], v[116:119]
	v_mfma_f32_16x16x32_bf16 v[112:115], v[154:157], v[170:173], v[112:115]
	v_mfma_f32_16x16x32_bf16 v[100:103], v[146:149], v[190:193], v[100:103]
	v_mfma_f32_16x16x32_bf16 v[96:99], v[154:157], v[190:193], v[96:99]
	v_mfma_f32_16x16x32_bf16 v[84:87], v[146:149], v[198:201], v[84:87]
	v_mfma_f32_16x16x32_bf16 v[80:83], v[154:157], v[198:201], v[80:83]
	s_barrier
	s_add_i32 s48, 0, 0x14000
	v_add_u32_e32 v174, s48, v139
	s_add_i32 s46, s46, s20
	ds_read_b128 v[202:205], v174
	ds_read_b128 v[206:209], v174 offset:1024
	ds_read_b128 v[210:213], v174 offset:2048
	ds_read_b128 v[214:217], v174 offset:3072
	s_add_u32 s98, s14, 0x80
	s_addc_u32 s99, s15, 0
	s_mov_b32 m0, s46
	s_nop 0
	global_load_lds_dwordx4 v176, s[14:15]
	s_add_i32 m0, s46, 0x2000
	s_nop 0
	global_load_lds_dwordx4 v128, s[14:15]
	s_barrier
	s_waitcnt lgkmcnt(0)
	v_mfma_f32_16x16x32_bf16 v[108:111], v[202:205], v[158:161], v[108:111]
	v_mfma_f32_16x16x32_bf16 v[104:107], v[210:213], v[158:161], v[104:107]
	v_mfma_f32_16x16x32_bf16 v[92:95], v[202:205], v[166:169], v[92:95]
	v_mfma_f32_16x16x32_bf16 v[88:91], v[210:213], v[166:169], v[88:91]
	v_mfma_f32_16x16x32_bf16 v[76:79], v[202:205], v[182:185], v[76:79]
	v_mfma_f32_16x16x32_bf16 v[72:75], v[210:213], v[182:185], v[72:75]
	v_mfma_f32_16x16x32_bf16 v[68:71], v[202:205], v[194:197], v[68:71]
	v_mfma_f32_16x16x32_bf16 v[64:67], v[210:213], v[194:197], v[64:67]
	v_mfma_f32_16x16x32_bf16 v[108:111], v[206:209], v[162:165], v[108:111]
	v_mfma_f32_16x16x32_bf16 v[104:107], v[214:217], v[162:165], v[104:107]
	v_mfma_f32_16x16x32_bf16 v[92:95], v[206:209], v[170:173], v[92:95]
	v_mfma_f32_16x16x32_bf16 v[88:91], v[214:217], v[170:173], v[88:91]
	v_mfma_f32_16x16x32_bf16 v[76:79], v[206:209], v[190:193], v[76:79]
	v_mfma_f32_16x16x32_bf16 v[72:75], v[214:217], v[190:193], v[72:75]
	v_mfma_f32_16x16x32_bf16 v[68:71], v[206:209], v[198:201], v[68:71]
	v_mfma_f32_16x16x32_bf16 v[64:67], v[214:217], v[198:201], v[64:67]
	s_mov_b32 m0, s1
	s_add_u32 s100, s16, 0x80
	s_addc_u32 s101, s17, 0
	s_barrier
	ds_read_b128 v[158:161], v141 offset:16384
	ds_read_b128 v[162:165], v141 offset:17408
	ds_read_b128 v[166:169], v141 offset:18432
	ds_read_b128 v[170:173], v141 offset:19456
	ds_read_b128 v[182:185], v141 offset:20480
	ds_read_b128 v[190:193], v141 offset:21504
	ds_read_b128 v[194:197], v141 offset:22528
	ds_read_b128 v[198:201], v141 offset:23552
	global_load_lds_dwordx4 v132, s[16:17]
	s_mov_b32 m0, s22
	s_nop 0
	global_load_lds_dwordx4 v130, s[16:17]
	s_barrier
	s_waitcnt lgkmcnt(0)
	v_mfma_f32_16x16x32_bf16 v[60:63], v[142:145], v[158:161], v[60:63]
	v_mfma_f32_16x16x32_bf16 v[56:59], v[150:153], v[158:161], v[56:59]
	v_mfma_f32_16x16x32_bf16 v[52:55], v[142:145], v[166:169], v[52:55]
	v_mfma_f32_16x16x32_bf16 v[48:51], v[150:153], v[166:169], v[48:51]
	v_mfma_f32_16x16x32_bf16 v[36:39], v[142:145], v[182:185], v[36:39]
	v_mfma_f32_16x16x32_bf16 v[32:35], v[150:153], v[182:185], v[32:35]
	v_mfma_f32_16x16x32_bf16 v[20:23], v[142:145], v[194:197], v[20:23]
	v_mfma_f32_16x16x32_bf16 v[16:19], v[150:153], v[194:197], v[16:19]
	v_mfma_f32_16x16x32_bf16 v[60:63], v[146:149], v[162:165], v[60:63]
	v_mfma_f32_16x16x32_bf16 v[56:59], v[154:157], v[162:165], v[56:59]
	v_mfma_f32_16x16x32_bf16 v[52:55], v[146:149], v[170:173], v[52:55]
	v_mfma_f32_16x16x32_bf16 v[48:51], v[154:157], v[170:173], v[48:51]
	v_mfma_f32_16x16x32_bf16 v[36:39], v[146:149], v[190:193], v[36:39]
	v_mfma_f32_16x16x32_bf16 v[32:35], v[154:157], v[190:193], v[32:35]
	v_mfma_f32_16x16x32_bf16 v[20:23], v[146:149], v[198:201], v[20:23]
	v_mfma_f32_16x16x32_bf16 v[16:19], v[154:157], v[198:201], v[16:19]
	s_barrier
	s_add_u32 s46, s14, 0x40000
	s_addc_u32 s47, s15, 0
	s_add_i32 s48, s48, s20
	s_mov_b32 m0, s48
	s_nop 0
	global_load_lds_dwordx4 v176, s[46:47]
	s_add_i32 m0, s48, 0x2000
	s_nop 0
	global_load_lds_dwordx4 v128, s[46:47]
	s_waitcnt vmcnt(6)
	s_barrier
; #define PG8_STAGE(bufoff, gbase, voff) do { _Pragma("unroll") for (int _i = 0; _i < 2; ++_i) \
;         __builtin_amdgcn_global_load_lds((const unsigned*)((const char*)(gbase) + (voff)[_i]), (PG8_LAS unsigned*)(lds + (bufoff) + ldsw + _i * 8192), 16, 0, 0); } while (0)
; #define PG8_LDA(dst, b, h) do { _Pragma("unroll") for (int m = 0; m < 4; ++m) _Pragma("unroll") for (int k = 0; k < 2; ++k) dst[m][k] = *(const PG8_LAS bf16x8*)(lds + PG8_SA(b, h) + aoff + m * 2048 + k * 1024); } while (0)
; #define PG8_LDB(dst, b, h) do { _Pragma("unroll") for (int n = 0; n < 2; ++n) _Pragma("unroll") for (int k = 0; k < 2; ++k) dst[n][k] = *(const PG8_LAS bf16x8*)(lds + PG8_SB(b, h) + boff + n * 2048 + k * 1024); } while (0)
; #define PG8_MMA(ai, bj, At, Bt) do { __builtin_amdgcn_s_setprio(1); _Pragma("unroll") for (int m = 0; m < 4; ++m) _Pragma("unroll") for (int n = 0; n < 2; ++n) _Pragma("unroll") for (int k = 0; k < 2; ++k) \
;         acc[ai][bj][m][n] = __builtin_amdgcn_mfma_f32_16x16x32_bf16(Bt[n][k], At[m][k], acc[ai][bj][m][n], 0, 0, 0); __builtin_amdgcn_s_setprio(0); } while (0)
; #define PG8_WAIT_V(n) asm volatile("s_waitcnt vmcnt(" #n ")" ::: "memory")
; #define PG8_WAIT_L(n) asm volatile("s_waitcnt lgkmcnt(" #n ")" ::: "memory")
; #define PG8_BAR __builtin_amdgcn_s_barrier()
; #define PG8_SCHED __builtin_amdgcn_sched_barrier(0)
; template <class Epi, class Sched>
; __device__ __forceinline__ void gemm_phase(PG8_LAS unsigned char* lds, const Gemm g, const Sched& S, const Epi& E) {
;     ...
;             PG8_WAIT_V(6); PG8_BAR; PG8_MMA(1, 1, At, B1); PG8_BAR;
;             PG8_LDB(B0, 1, 0); PG8_SCHED; PG8_LDA(At, 1, 0); PG8_STAGE(PG8_SA(0, 1), a2 + hstep, voffA);
;             PG8_WAIT_L(8); PG8_BAR; PG8_WAIT_L(0); PG8_MMA(0, 0, At, B0); PG8_BAR; PG8_SCHED;
;             PG8_LDB(B1, 1, 1); PG8_STAGE(PG8_SB(1, 0), b3, voffB);
;             PG8_BAR; PG8_WAIT_L(0); PG8_MMA(0, 1, At, B1); PG8_BAR;
;             PG8_LDA(At, 1, 1); PG8_STAGE(PG8_SA(1, 0), a3, voffA);
	v_mfma_f32_16x16x32_bf16 v[44:47], v[202:205], v[158:161], v[44:47]
	v_mfma_f32_16x16x32_bf16 v[40:43], v[210:213], v[158:161], v[40:43]
	v_mfma_f32_16x16x32_bf16 v[28:31], v[202:205], v[166:169], v[28:31]
	v_mfma_f32_16x16x32_bf16 v[24:27], v[210:213], v[166:169], v[24:27]
	v_mfma_f32_16x16x32_bf16 v[12:15], v[202:205], v[182:185], v[12:15]
	v_mfma_f32_16x16x32_bf16 v[8:11], v[210:213], v[182:185], v[8:11]
	v_mfma_f32_16x16x32_bf16 v[4:7], v[202:205], v[194:197], v[4:7]
	v_mfma_f32_16x16x32_bf16 v[0:3], v[210:213], v[194:197], v[0:3]
	v_mfma_f32_16x16x32_bf16 v[44:47], v[206:209], v[162:165], v[44:47]
	v_mfma_f32_16x16x32_bf16 v[40:43], v[214:217], v[162:165], v[40:43]
	v_mfma_f32_16x16x32_bf16 v[28:31], v[206:209], v[170:173], v[28:31]
	v_mfma_f32_16x16x32_bf16 v[24:27], v[214:217], v[170:173], v[24:27]
	v_mfma_f32_16x16x32_bf16 v[12:15], v[206:209], v[190:193], v[12:15]
	v_mfma_f32_16x16x32_bf16 v[8:11], v[214:217], v[190:193], v[8:11]
	v_mfma_f32_16x16x32_bf16 v[4:7], v[206:209], v[198:201], v[4:7]
	v_mfma_f32_16x16x32_bf16 v[0:3], v[214:217], v[198:201], v[0:3]
	s_add_i32 s46, 0, 0x18000
	v_add_u32_e32 v154, s46, v139
	s_barrier
	ds_read_b128 v[142:145], v154
	ds_read_b128 v[146:149], v154 offset:1024
	ds_read_b128 v[150:153], v154 offset:2048
	ds_read_b128 v[154:157], v154 offset:3072
	s_add_u32 s16, s16, 0x40000
	s_addc_u32 s17, s17, 0
	s_mov_b32 m0, s23
	ds_read_b128 v[158:161], v141 offset:32768
	ds_read_b128 v[162:165], v141 offset:33792
	ds_read_b128 v[166:169], v141 offset:34816
	ds_read_b128 v[170:173], v141 offset:35840
	ds_read_b128 v[182:185], v141 offset:36864
	ds_read_b128 v[190:193], v141 offset:37888
	ds_read_b128 v[194:197], v141 offset:38912
	ds_read_b128 v[198:201], v141 offset:39936
	global_load_lds_dwordx4 v132, s[16:17]
	s_mov_b32 m0, s26
	s_nop 0
	global_load_lds_dwordx4 v130, s[16:17]
	s_waitcnt lgkmcnt(8)
	s_barrier
	s_waitcnt lgkmcnt(0)
	v_mfma_f32_16x16x32_bf16 v[124:127], v[142:145], v[158:161], v[124:127]
	v_mfma_f32_16x16x32_bf16 v[120:123], v[150:153], v[158:161], v[120:123]
	v_mfma_f32_16x16x32_bf16 v[116:119], v[142:145], v[166:169], v[116:119]
	v_mfma_f32_16x16x32_bf16 v[112:115], v[150:153], v[166:169], v[112:115]
	v_mfma_f32_16x16x32_bf16 v[100:103], v[142:145], v[182:185], v[100:103]
	v_mfma_f32_16x16x32_bf16 v[96:99], v[150:153], v[182:185], v[96:99]
	v_mfma_f32_16x16x32_bf16 v[84:87], v[142:145], v[194:197], v[84:87]
	v_mfma_f32_16x16x32_bf16 v[80:83], v[150:153], v[194:197], v[80:83]
	v_mfma_f32_16x16x32_bf16 v[124:127], v[146:149], v[162:165], v[124:127]
	v_mfma_f32_16x16x32_bf16 v[120:123], v[154:157], v[162:165], v[120:123]
	v_mfma_f32_16x16x32_bf16 v[116:119], v[146:149], v[170:173], v[116:119]
	v_mfma_f32_16x16x32_bf16 v[112:115], v[154:157], v[170:173], v[112:115]
	v_mfma_f32_16x16x32_bf16 v[100:103], v[146:149], v[190:193], v[100:103]
	v_mfma_f32_16x16x32_bf16 v[96:99], v[154:157], v[190:193], v[96:99]
	v_mfma_f32_16x16x32_bf16 v[84:87], v[146:149], v[198:201], v[84:87]
	v_mfma_f32_16x16x32_bf16 v[80:83], v[154:157], v[198:201], v[80:83]
	s_barrier
	s_add_i32 s16, 0, 0x1c000
	s_add_i32 s17, s46, s20
	v_add_u32_e32 v188, s16, v139
	s_mov_b32 m0, s17
	ds_read_b128 v[202:205], v188
	ds_read_b128 v[206:209], v188 offset:1024
	ds_read_b128 v[210:213], v188 offset:2048
	ds_read_b128 v[214:217], v188 offset:3072
	global_load_lds_dwordx4 v176, s[98:99]
	s_add_i32 m0, s17, 0x2000
	s_nop 0
	global_load_lds_dwordx4 v128, s[98:99]
	s_barrier
	s_waitcnt lgkmcnt(0)
	v_mfma_f32_16x16x32_bf16 v[108:111], v[202:205], v[158:161], v[108:111]
	v_mfma_f32_16x16x32_bf16 v[104:107], v[210:213], v[158:161], v[104:107]
	v_mfma_f32_16x16x32_bf16 v[92:95], v[202:205], v[166:169], v[92:95]
	v_mfma_f32_16x16x32_bf16 v[88:91], v[210:213], v[166:169], v[88:91]
	v_mfma_f32_16x16x32_bf16 v[76:79], v[202:205], v[182:185], v[76:79]
	v_mfma_f32_16x16x32_bf16 v[72:75], v[210:213], v[182:185], v[72:75]
	v_mfma_f32_16x16x32_bf16 v[68:71], v[202:205], v[194:197], v[68:71]
	v_mfma_f32_16x16x32_bf16 v[64:67], v[210:213], v[194:197], v[64:67]
	v_mfma_f32_16x16x32_bf16 v[108:111], v[206:209], v[162:165], v[108:111]
	v_mfma_f32_16x16x32_bf16 v[104:107], v[214:217], v[162:165], v[104:107]
	v_mfma_f32_16x16x32_bf16 v[92:95], v[206:209], v[170:173], v[92:95]
	v_mfma_f32_16x16x32_bf16 v[88:91], v[214:217], v[170:173], v[88:91]
	v_mfma_f32_16x16x32_bf16 v[76:79], v[206:209], v[190:193], v[76:79]
	v_mfma_f32_16x16x32_bf16 v[72:75], v[214:217], v[190:193], v[72:75]
	v_mfma_f32_16x16x32_bf16 v[68:71], v[206:209], v[198:201], v[68:71]
	v_mfma_f32_16x16x32_bf16 v[64:67], v[214:217], v[198:201], v[64:67]
	s_mov_b32 m0, s28
	s_barrier
	ds_read_b128 v[158:161], v141 offset:49152
	ds_read_b128 v[162:165], v141 offset:50176
	ds_read_b128 v[166:169], v141 offset:51200
	ds_read_b128 v[170:173], v141 offset:52224
	ds_read_b128 v[182:185], v141 offset:53248
	ds_read_b128 v[190:193], v141 offset:54272
	ds_read_b128 v[194:197], v141 offset:55296
	ds_read_b128 v[198:201], v141 offset:56320
	global_load_lds_dwordx4 v132, s[100:101]
	s_mov_b32 m0, s29
	s_nop 0
	global_load_lds_dwordx4 v130, s[100:101]
	s_barrier
; #define PG8_STAGE(bufoff, gbase, voff) do { _Pragma("unroll") for (int _i = 0; _i < 2; ++_i) \
;         __builtin_amdgcn_global_load_lds((const unsigned*)((const char*)(gbase) + (voff)[_i]), (PG8_LAS unsigned*)(lds + (bufoff) + ldsw + _i * 8192), 16, 0, 0); } while (0)
; #define PG8_LDA(dst, b, h) do { _Pragma("unroll") for (int m = 0; m < 4; ++m) _Pragma("unroll") for (int k = 0; k < 2; ++k) dst[m][k] = *(const PG8_LAS bf16x8*)(lds + PG8_SA(b, h) + aoff + m * 2048 + k * 1024); } while (0)
; #define PG8_MMA(ai, bj, At, Bt) do { __builtin_amdgcn_s_setprio(1); _Pragma("unroll") for (int m = 0; m < 4; ++m) _Pragma("unroll") for (int n = 0; n < 2; ++n) _Pragma("unroll") for (int k = 0; k < 2; ++k) \
;         acc[ai][bj][m][n] = __builtin_amdgcn_mfma_f32_16x16x32_bf16(Bt[n][k], At[m][k], acc[ai][bj][m][n], 0, 0, 0); __builtin_amdgcn_s_setprio(0); } while (0)
; #define PG8_WAIT_V(n) asm volatile("s_waitcnt vmcnt(" #n ")" ::: "memory")
; #define PG8_WAIT_L(n) asm volatile("s_waitcnt lgkmcnt(" #n ")" ::: "memory")
; #define PG8_BAR __builtin_amdgcn_s_barrier()
; #define PG8_SCHED __builtin_amdgcn_sched_barrier(0)
; template <class Epi, class Sched>
; __device__ __forceinline__ void gemm_phase(PG8_LAS unsigned char* lds, const Gemm g, const Sched& S, const Epi& E) {
;     ...
;             PG8_LDA(At, 1, 1); PG8_STAGE(PG8_SA(1, 0), a3, voffA);
;             PG8_BAR; PG8_WAIT_L(0); PG8_MMA(1, 0, At, B0); PG8_BAR; PG8_SCHED;
;             PG8_STAGE(PG8_SB(1, 1), b3 + hstep, voffB);
;             PG8_WAIT_V(6); PG8_BAR; PG8_MMA(1, 1, At, B1); PG8_BAR;
;         }
	s_waitcnt lgkmcnt(0)
	v_mfma_f32_16x16x32_bf16 v[60:63], v[142:145], v[158:161], v[60:63]
	v_mfma_f32_16x16x32_bf16 v[56:59], v[150:153], v[158:161], v[56:59]
	v_mfma_f32_16x16x32_bf16 v[52:55], v[142:145], v[166:169], v[52:55]
	v_mfma_f32_16x16x32_bf16 v[48:51], v[150:153], v[166:169], v[48:51]
	v_mfma_f32_16x16x32_bf16 v[36:39], v[142:145], v[182:185], v[36:39]
	v_mfma_f32_16x16x32_bf16 v[32:35], v[150:153], v[182:185], v[32:35]
	v_mfma_f32_16x16x32_bf16 v[20:23], v[142:145], v[194:197], v[20:23]
	v_mfma_f32_16x16x32_bf16 v[16:19], v[150:153], v[194:197], v[16:19]
	v_mfma_f32_16x16x32_bf16 v[60:63], v[146:149], v[162:165], v[60:63]
	v_mfma_f32_16x16x32_bf16 v[56:59], v[154:157], v[162:165], v[56:59]
	v_mfma_f32_16x16x32_bf16 v[52:55], v[146:149], v[170:173], v[52:55]
	v_mfma_f32_16x16x32_bf16 v[48:51], v[154:157], v[170:173], v[48:51]
	v_mfma_f32_16x16x32_bf16 v[36:39], v[146:149], v[190:193], v[36:39]
	v_mfma_f32_16x16x32_bf16 v[32:35], v[154:157], v[190:193], v[32:35]
	v_mfma_f32_16x16x32_bf16 v[20:23], v[146:149], v[198:201], v[20:23]
	v_mfma_f32_16x16x32_bf16 v[16:19], v[154:157], v[198:201], v[16:19]
	s_barrier
	s_add_u32 s14, s14, 0x40080
	s_addc_u32 s15, s15, 0
	s_add_i32 s16, s16, s20
	s_mov_b32 m0, s16
	s_nop 0
	global_load_lds_dwordx4 v176, s[14:15]
	s_add_i32 m0, s16, 0x2000
	s_nop 0
	global_load_lds_dwordx4 v128, s[14:15]
	s_waitcnt vmcnt(6)
	s_barrier
	v_mfma_f32_16x16x32_bf16 v[44:47], v[202:205], v[158:161], v[44:47]
	v_mfma_f32_16x16x32_bf16 v[40:43], v[210:213], v[158:161], v[40:43]
	v_mfma_f32_16x16x32_bf16 v[28:31], v[202:205], v[166:169], v[28:31]
	v_mfma_f32_16x16x32_bf16 v[24:27], v[210:213], v[166:169], v[24:27]
	v_mfma_f32_16x16x32_bf16 v[12:15], v[202:205], v[182:185], v[12:15]
	v_mfma_f32_16x16x32_bf16 v[8:11], v[210:213], v[182:185], v[8:11]
	v_mfma_f32_16x16x32_bf16 v[4:7], v[202:205], v[194:197], v[4:7]
	v_mfma_f32_16x16x32_bf16 v[0:3], v[210:213], v[194:197], v[0:3]
	v_mfma_f32_16x16x32_bf16 v[44:47], v[206:209], v[162:165], v[44:47]
	v_mfma_f32_16x16x32_bf16 v[40:43], v[214:217], v[162:165], v[40:43]
	v_mfma_f32_16x16x32_bf16 v[28:31], v[206:209], v[170:173], v[28:31]
	v_mfma_f32_16x16x32_bf16 v[24:27], v[214:217], v[170:173], v[24:27]
	v_mfma_f32_16x16x32_bf16 v[12:15], v[206:209], v[190:193], v[12:15]
	v_mfma_f32_16x16x32_bf16 v[8:11], v[214:217], v[190:193], v[8:11]
	v_mfma_f32_16x16x32_bf16 v[4:7], v[206:209], v[198:201], v[4:7]
	v_mfma_f32_16x16x32_bf16 v[0:3], v[214:217], v[198:201], v[0:3]
	s_add_i32 s45, s45, 2
	s_add_u32 s12, s12, 0x100
	s_addc_u32 s13, s13, 0
	s_add_u32 s43, s43, 0x100
	s_addc_u32 s44, s44, 0
	s_cmp_gt_u32 s45, 13
	s_barrier
	s_cbranch_scc0 .LBB0_358
; __device__ __forceinline__ unsigned cvtpk(float lo, float hi) { const f32x2 v = (f32x2){lo, hi}; const bf16v2 b = __builtin_convertvector(v, bf16v2); return __builtin_bit_cast(unsigned, b); }
; #define PG8_WAIT_V(n) asm volatile("s_waitcnt vmcnt(" #n ")" ::: "memory")
; #define PG8_BAR __builtin_amdgcn_s_barrier()
; template <class Epi, class Sched>
; __device__ __forceinline__ void gemm_phase(PG8_LAS unsigned char* lds, const Gemm g, const Sched& S, const Epi& E) {
;     ...
;         if constexpr (!Epi::AFTER_DRAIN) { E(acc, cur, wr, wc, fr, fq); S.done(cur); }
;         if (!has_next) break;
; #pragma unroll
;         for (int a = 0; a < 2; ++a)
; #pragma unroll
;             for (int b = 0; b < 2; ++b)
; #pragma unroll
;                 for (int m = 0; m < 4; ++m)
; #pragma unroll
;                     for (int n = 0; n < 2; ++n) acc[a][b][m][n] = (f32x4){0.f, 0.f, 0.f, 0.f};
;         cur = nxt; cA = nA; cB = nB; ++ui;
;     }
;     PG8_WAIT_V(0);
;     if (wr == 0) PG8_BAR;
;     PG8_BAR;
;     __device__ __forceinline__ void operator()(const f32x4 (&acc)[2][2][4][2], const pg8::Unit& u, int wr, int wc, int fr, int fq) const {
;         const int row0 = u.pm * 256 + wr * 64 + fr, col0 = u.pn * 256 + wc * 32 + 8 * fq;
; #pragma unroll
;         for (int ai = 0; ai < 2; ++ai)
; #pragma unroll
;             for (int m = 0; m < 4; ++m) { bf16_t* rowp = O + (size_t)(row0 + ai * 128 + m * 16) * ldc + col0;
; #pragma unroll
;                 for (int bj = 0; bj < 2; ++bj) { const f32x4 v0 = acc[ai][bj][m][0], v1 = acc[ai][bj][m][1];
;                     u32x4 w; w.x = cvtpk(v0[0], v0[1]); w.y = cvtpk(v0[2], v0[3]); w.z = cvtpk(v1[0], v1[1]); w.w = cvtpk(v1[2], v1[3]);
;                     *(u32x4*)(rowp + bj * 128) = w; } }
	v_readlane_b32 s12, v253, 16
	v_lshl_add_u32 v148, s0, 8, v138
	v_lshl_or_b32 v142, s34, 8, v140
	v_readlane_b32 s13, v253, 17
	v_ashrrev_i32_e32 v143, 31, v142
	v_cvt_pk_bf16_f32 v68, v68, v69
	v_mov_b64_e32 v[144:145], s[12:13]
	v_cvt_pk_bf16_f32 v69, v70, v71
	v_cvt_pk_bf16_f32 v70, v64, v65
	v_add_u32_e32 v64, 0x80, v148
	v_mad_i64_i32 v[146:147], s[12:13], v148, s81, v[144:145]
	v_lshlrev_b64 v[142:143], 1, v[142:143]
	v_cvt_pk_bf16_f32 v108, v108, v109
	v_cvt_pk_bf16_f32 v109, v110, v111
	v_cvt_pk_bf16_f32 v110, v104, v105
	v_or_b32_e32 v104, 16, v148
	v_mad_i64_i32 v[64:65], s[12:13], v64, s81, v[144:145]
	v_cvt_pk_bf16_f32 v44, v44, v45
	v_cvt_pk_bf16_f32 v45, v46, v47
	v_cvt_pk_bf16_f32 v46, v40, v41
	v_add_u32_e32 v40, 0x90, v148
	v_lshl_add_u64 v[146:147], v[146:147], 0, v[142:143]
	v_cvt_pk_bf16_f32 v111, v106, v107
	v_mad_i64_i32 v[104:105], s[12:13], v104, s81, v[144:145]
	v_cvt_pk_bf16_f32 v92, v92, v93
	v_cvt_pk_bf16_f32 v93, v94, v95
	v_cvt_pk_bf16_f32 v94, v88, v89
	v_or_b32_e32 v88, 32, v148
	v_lshl_add_u64 v[64:65], v[64:65], 0, v[142:143]
	v_cvt_pk_bf16_f32 v47, v42, v43
	v_mad_i64_i32 v[40:41], s[12:13], v40, s81, v[144:145]
	v_cvt_pk_bf16_f32 v28, v28, v29
	v_cvt_pk_bf16_f32 v29, v30, v31
	v_cvt_pk_bf16_f32 v30, v24, v25
	v_add_u32_e32 v24, 0xa0, v148
	global_store_dwordx4 v[146:147], v[108:111], off offset:256
	v_cvt_pk_bf16_f32 v95, v90, v91
	v_mad_i64_i32 v[88:89], s[12:13], v88, s81, v[144:145]
	v_lshl_add_u64 v[108:109], v[104:105], 0, v[142:143]
	v_cvt_pk_bf16_f32 v76, v76, v77
	v_cvt_pk_bf16_f32 v77, v78, v79
	v_cvt_pk_bf16_f32 v78, v72, v73
	v_or_b32_e32 v72, 48, v148
	global_store_dwordx4 v[64:65], v[44:47], off offset:256
	v_cvt_pk_bf16_f32 v31, v26, v27
	v_mad_i64_i32 v[24:25], s[12:13], v24, s81, v[144:145]
	v_lshl_add_u64 v[44:45], v[40:41], 0, v[142:143]
	v_cvt_pk_bf16_f32 v12, v12, v13
	v_cvt_pk_bf16_f32 v13, v14, v15
	v_cvt_pk_bf16_f32 v14, v8, v9
	v_add_u32_e32 v8, 0xb0, v148
	global_store_dwordx4 v[108:109], v[92:95], off offset:256
	v_cvt_pk_bf16_f32 v79, v74, v75
	v_mad_i64_i32 v[72:73], s[12:13], v72, s81, v[144:145]
	v_lshl_add_u64 v[92:93], v[88:89], 0, v[142:143]
	global_store_dwordx4 v[44:45], v[28:31], off offset:256
	v_cvt_pk_bf16_f32 v15, v10, v11
	v_mad_i64_i32 v[8:9], s[12:13], v8, s81, v[144:145]
	v_lshl_add_u64 v[28:29], v[24:25], 0, v[142:143]
	v_cvt_pk_bf16_f32 v124, v124, v125
	v_cvt_pk_bf16_f32 v125, v126, v127
	v_cvt_pk_bf16_f32 v126, v120, v121
	v_cvt_pk_bf16_f32 v127, v122, v123
	v_cvt_pk_bf16_f32 v104, v116, v117
	v_cvt_pk_bf16_f32 v105, v118, v119
	v_cvt_pk_bf16_f32 v106, v112, v113
	v_cvt_pk_bf16_f32 v107, v114, v115
	v_cvt_pk_bf16_f32 v88, v100, v101
	v_cvt_pk_bf16_f32 v89, v102, v103
	v_cvt_pk_bf16_f32 v90, v96, v97
	v_cvt_pk_bf16_f32 v91, v98, v99
	global_store_dwordx4 v[92:93], v[76:79], off offset:256
	v_cvt_pk_bf16_f32 v74, v80, v81
	v_cvt_pk_bf16_f32 v75, v82, v83
	v_lshl_add_u64 v[76:77], v[72:73], 0, v[142:143]
	v_cvt_pk_bf16_f32 v72, v84, v85
	v_cvt_pk_bf16_f32 v73, v86, v87
	v_cvt_pk_bf16_f32 v71, v66, v67
	v_cvt_pk_bf16_f32 v60, v60, v61
	v_cvt_pk_bf16_f32 v61, v62, v63
	v_cvt_pk_bf16_f32 v62, v56, v57
	v_cvt_pk_bf16_f32 v63, v58, v59
	v_cvt_pk_bf16_f32 v40, v52, v53
	v_cvt_pk_bf16_f32 v41, v54, v55
	v_cvt_pk_bf16_f32 v42, v48, v49
	v_cvt_pk_bf16_f32 v43, v50, v51
	v_cvt_pk_bf16_f32 v24, v36, v37
	v_cvt_pk_bf16_f32 v25, v38, v39
	v_cvt_pk_bf16_f32 v26, v32, v33
	v_cvt_pk_bf16_f32 v27, v34, v35
	global_store_dwordx4 v[28:29], v[12:15], off offset:256
	v_cvt_pk_bf16_f32 v10, v16, v17
	v_cvt_pk_bf16_f32 v11, v18, v19
	v_lshl_add_u64 v[12:13], v[8:9], 0, v[142:143]
	v_cvt_pk_bf16_f32 v8, v20, v21
	v_cvt_pk_bf16_f32 v9, v22, v23
	v_cvt_pk_bf16_f32 v4, v4, v5
	v_cvt_pk_bf16_f32 v5, v6, v7
	v_cvt_pk_bf16_f32 v6, v0, v1
	v_cvt_pk_bf16_f32 v7, v2, v3
	s_and_b64 vcc, exec, s[38:39]
	s_mov_b32 s34, s4
	s_mov_b32 s0, s6
	s_mov_b64 s[14:15], s[10:11]
	s_mov_b64 s[12:13], s[8:9]
	global_store_dwordx4 v[146:147], v[124:127], off
	global_store_dwordx4 v[108:109], v[104:107], off
	global_store_dwordx4 v[92:93], v[88:91], off
	global_store_dwordx4 v[76:77], v[72:75], off
	global_store_dwordx4 v[76:77], v[68:71], off offset:256
	global_store_dwordx4 v[64:65], v[60:63], off
	global_store_dwordx4 v[44:45], v[40:43], off
	global_store_dwordx4 v[28:29], v[24:27], off
	global_store_dwordx4 v[12:13], v[8:11], off
	global_store_dwordx4 v[12:13], v[4:7], off offset:256
	s_cbranch_vccz .LBB0_355
	s_waitcnt vmcnt(0)
	v_readlane_b32 s22, v255, 14
	s_cmpk_gt_u32 s19, 0xff
	v_readlane_b32 s23, v255, 15
	s_mov_b64 s[28:29], s[54:55]
	s_cbranch_scc1 .LBB0_362
	s_barrier
